# GEMM MFMA phases: redundant s_waitcnt lgkmcnt(0) after the barrier removed (the same wait precedes the barrier)
# speedup vs baseline: 1.0125x; 1.0034x over previous
; #define PG8_STAGE(bufoff, gbase, voff) do { _Pragma("unroll") for (int _i = 0; _i < 2; ++_i) \
;         __builtin_amdgcn_global_load_lds((const unsigned*)((const char*)(gbase) + (voff)[_i]), (LAS unsigned*)(lds + (bufoff) + ldsw + _i * 8192), 16, 0, 0); } while (0)
; #define PG8_LDA(dst, b, h) do { _Pragma("unroll") for (int m = 0; m < 4; ++m) _Pragma("unroll") for (int k = 0; k < 2; ++k) dst[m][k] = *(const LAS bf16x8*)(lds + PG8_SA(b, h) + aoff + m * 2048 + k * 1024); } while (0)
; #define PG8_LDB(dst, b, h) do { _Pragma("unroll") for (int n = 0; n < 2; ++n) _Pragma("unroll") for (int k = 0; k < 2; ++k) dst[n][k] = *(const LAS bf16x8*)(lds + PG8_SB(b, h) + boff + n * 2048 + k * 1024); } while (0)
; #define PG8_MMA(ai, bj, At, Bt) do { __builtin_amdgcn_s_setprio(1); _Pragma("unroll") for (int m = 0; m < 4; ++m) _Pragma("unroll") for (int n = 0; n < 2; ++n) _Pragma("unroll") for (int k = 0; k < 2; ++k) \
;         acc[ai][bj][m][n] = __builtin_amdgcn_mfma_f32_16x16x32_bf16(Bt[n][k], At[m][k], acc[ai][bj][m][n], 0, 0, 0); __builtin_amdgcn_s_setprio(0); } while (0)
; #define PG8_WAIT_V(n) asm volatile("s_waitcnt vmcnt(" #n ")" ::: "memory")
; #define PG8_WAIT_L(n) asm volatile("s_waitcnt lgkmcnt(" #n ")" ::: "memory")
; #define PG8_BAR __builtin_amdgcn_s_barrier()
; #define PG8_SCHED __builtin_amdgcn_sched_barrier(0)
; template <class Epi, class Sched>
; __device__ __forceinline__ void gemm_phase(LAS unsigned char* lds, const int lda, const int ldb, const int K, const Sched& S, const Epi& E, int tid) {
;     ...
;             const bool last = (t == nt - 2);
;             const char* a1 = cA + (size_t)(t + 1) * kstep;
;             const char* a2 = last ? nA : cA + (size_t)(t + 2) * kstep; const char* b2 = last ? nB : cB + (size_t)(t + 2) * kstep;
;             const char* a3 = a2 + kstep; const char* b3 = b2 + kstep;
;             PG8_LDB(B0, 0, 0); PG8_LDB(B1, 0, 1); PG8_SCHED; PG8_LDA(At, 0, 0); PG8_STAGE(PG8_SA(1, 1), a1 + hA, voffA);
;             PG8_WAIT_V(8); PG8_WAIT_L(0); PG8_BAR; PG8_MMA(0, 0, At, B0); PG8_MMA(0, 1, At, B1); PG8_BAR; PG8_SCHED;
;             PG8_LDA(At, 0, 1); PG8_STAGE(PG8_SB(0, 0), b2, voffB); PG8_STAGE(PG8_SB(0, 1), b2 + hB, voffB); PG8_STAGE(PG8_SA(0, 0), a2, voffA);
;             PG8_WAIT_V(8); PG8_WAIT_L(0); PG8_BAR; PG8_MMA(1, 0, At, B0); PG8_MMA(1, 1, At, B1); PG8_BAR; PG8_SCHED;
.LBB0_91:
	s_add_u32 s10, s4, 0xfff80080
	s_addc_u32 s11, s5, -1
	s_add_i32 s22, 0, 0x10000
	s_cmp_eq_u32 s18, 28
	s_cselect_b32 s17, s3, s11
	s_cselect_b32 s16, s2, s10
	v_add_u32_e32 v0, s22, v174
	s_cselect_b32 s11, s15, s9
	s_cselect_b32 s10, s14, s7
	s_add_i32 s33, 0, 0x14000
	ds_read_b128 v[130:133], v0
	ds_read_b128 v[134:137], v0 offset:1024
	ds_read_b128 v[138:141], v0 offset:2048
	ds_read_b128 v[142:145], v0 offset:3072
	v_add_u32_e32 v0, s33, v174
	ds_read_b128 v[160:163], v0
	ds_read_b128 v[164:167], v0 offset:1024
	ds_read_b128 v[168:171], v0 offset:2048
	ds_read_b128 v[180:183], v0 offset:3072
	s_add_i32 m0, s21, 0xc000
	ds_read_b128 v[184:187], v178
	ds_read_b128 v[188:191], v178 offset:1024
	ds_read_b128 v[192:195], v178 offset:2048
	ds_read_b128 v[200:203], v178 offset:3072
	ds_read_b128 v[204:207], v178 offset:4096
	ds_read_b128 v[208:211], v178 offset:5120
	ds_read_b128 v[212:215], v178 offset:6144
	ds_read_b128 v[216:219], v178 offset:7168
	global_load_lds_dwordx4 v156, s[4:5]
	s_add_i32 m0, s21, 0xe000
	s_nop 0
	global_load_lds_dwordx4 v158, s[4:5]
	s_waitcnt vmcnt(8)
	s_waitcnt lgkmcnt(0)
	s_barrier
	s_setprio 1
	v_mfma_f32_16x16x32_bf16 v[126:129], v[130:133], v[184:187], v[126:129]
	v_mfma_f32_16x16x32_bf16 v[122:125], v[138:141], v[184:187], v[122:125]
	v_mfma_f32_16x16x32_bf16 v[118:121], v[130:133], v[192:195], v[118:121]
	v_mfma_f32_16x16x32_bf16 v[110:113], v[138:141], v[192:195], v[110:113]
	v_mfma_f32_16x16x32_bf16 v[102:105], v[130:133], v[204:207], v[102:105]
	v_mfma_f32_16x16x32_bf16 v[94:97], v[138:141], v[204:207], v[94:97]
	v_mfma_f32_16x16x32_bf16 v[86:89], v[130:133], v[212:215], v[86:89]
	v_mfma_f32_16x16x32_bf16 v[78:81], v[138:141], v[212:215], v[78:81]
	v_mfma_f32_16x16x32_bf16 v[126:129], v[134:137], v[188:191], v[126:129]
	v_mfma_f32_16x16x32_bf16 v[122:125], v[142:145], v[188:191], v[122:125]
	v_mfma_f32_16x16x32_bf16 v[118:121], v[134:137], v[200:203], v[118:121]
	v_mfma_f32_16x16x32_bf16 v[110:113], v[142:145], v[200:203], v[110:113]
	v_mfma_f32_16x16x32_bf16 v[102:105], v[134:137], v[208:211], v[102:105]
	v_mfma_f32_16x16x32_bf16 v[94:97], v[142:145], v[208:211], v[94:97]
	v_mfma_f32_16x16x32_bf16 v[86:89], v[134:137], v[216:219], v[86:89]
	v_mfma_f32_16x16x32_bf16 v[78:81], v[142:145], v[216:219], v[78:81]
	s_setprio 0
	s_setprio 1
	v_mfma_f32_16x16x32_bf16 v[114:117], v[160:163], v[184:187], v[114:117]
	v_mfma_f32_16x16x32_bf16 v[106:109], v[168:171], v[184:187], v[106:109]
	v_mfma_f32_16x16x32_bf16 v[98:101], v[160:163], v[192:195], v[98:101]
	v_mfma_f32_16x16x32_bf16 v[90:93], v[168:171], v[192:195], v[90:93]
	v_mfma_f32_16x16x32_bf16 v[82:85], v[160:163], v[204:207], v[82:85]
	v_mfma_f32_16x16x32_bf16 v[74:77], v[168:171], v[204:207], v[74:77]
	v_mfma_f32_16x16x32_bf16 v[70:73], v[160:163], v[212:215], v[70:73]
	v_mfma_f32_16x16x32_bf16 v[66:69], v[168:171], v[212:215], v[66:69]
	v_mfma_f32_16x16x32_bf16 v[114:117], v[164:167], v[188:191], v[114:117]
	v_mfma_f32_16x16x32_bf16 v[106:109], v[180:183], v[188:191], v[106:109]
	v_mfma_f32_16x16x32_bf16 v[98:101], v[164:167], v[200:203], v[98:101]
	v_mfma_f32_16x16x32_bf16 v[90:93], v[180:183], v[200:203], v[90:93]
	v_mfma_f32_16x16x32_bf16 v[82:85], v[164:167], v[208:211], v[82:85]
	v_mfma_f32_16x16x32_bf16 v[74:77], v[180:183], v[208:211], v[74:77]
	v_mfma_f32_16x16x32_bf16 v[70:73], v[164:167], v[216:219], v[70:73]
	v_mfma_f32_16x16x32_bf16 v[66:69], v[180:183], v[216:219], v[66:69]
	s_setprio 0
	s_barrier
	s_add_u32 s98, s10, s30
	s_addc_u32 s99, s11, s31
	s_add_u32 s100, s16, s30
	s_addc_u32 s101, s17, s31
	s_add_i32 s22, s22, s20
	s_mov_b32 m0, s22
	ds_read_b128 v[184:187], v178 offset:16384
	ds_read_b128 v[188:191], v178 offset:17408
	ds_read_b128 v[192:195], v178 offset:18432
	ds_read_b128 v[200:203], v178 offset:19456
	ds_read_b128 v[204:207], v178 offset:20480
	ds_read_b128 v[208:211], v178 offset:21504
	ds_read_b128 v[212:215], v178 offset:22528
	ds_read_b128 v[216:219], v178 offset:23552
	global_load_lds_dwordx4 v148, s[10:11]
	s_add_i32 m0, s22, 0x2000
	s_add_u32 s22, s10, 0x80000
	s_addc_u32 s23, s11, 0
	s_add_i32 s33, s33, s20
	global_load_lds_dwordx4 v152, s[10:11]
	s_mov_b32 m0, s33
	s_nop 0
	global_load_lds_dwordx4 v148, s[22:23]
	s_add_i32 m0, s33, 0x2000
	s_nop 0
	global_load_lds_dwordx4 v152, s[22:23]
	s_mov_b32 m0, s21
	s_nop 0
	global_load_lds_dwordx4 v146, s[16:17]
	s_mov_b32 m0, s25
	s_nop 0
	global_load_lds_dwordx4 v150, s[16:17]
	s_waitcnt vmcnt(8)
	s_waitcnt lgkmcnt(0)
	s_barrier
	s_setprio 1
	v_mfma_f32_16x16x32_bf16 v[62:65], v[130:133], v[184:187], v[62:65]
	v_mfma_f32_16x16x32_bf16 v[58:61], v[138:141], v[184:187], v[58:61]
	v_mfma_f32_16x16x32_bf16 v[54:57], v[130:133], v[192:195], v[54:57]
	v_mfma_f32_16x16x32_bf16 v[46:49], v[138:141], v[192:195], v[46:49]
	v_mfma_f32_16x16x32_bf16 v[38:41], v[130:133], v[204:207], v[38:41]
	v_mfma_f32_16x16x32_bf16 v[30:33], v[138:141], v[204:207], v[30:33]
	v_mfma_f32_16x16x32_bf16 v[22:25], v[130:133], v[212:215], v[22:25]
	v_mfma_f32_16x16x32_bf16 v[14:17], v[138:141], v[212:215], v[14:17]
	v_mfma_f32_16x16x32_bf16 v[62:65], v[134:137], v[188:191], v[62:65]
	v_mfma_f32_16x16x32_bf16 v[58:61], v[142:145], v[188:191], v[58:61]
	v_mfma_f32_16x16x32_bf16 v[54:57], v[134:137], v[200:203], v[54:57]
	v_mfma_f32_16x16x32_bf16 v[46:49], v[142:145], v[200:203], v[46:49]
	v_mfma_f32_16x16x32_bf16 v[38:41], v[134:137], v[208:211], v[38:41]
	v_mfma_f32_16x16x32_bf16 v[30:33], v[142:145], v[208:211], v[30:33]
	v_mfma_f32_16x16x32_bf16 v[22:25], v[134:137], v[216:219], v[22:25]
	v_mfma_f32_16x16x32_bf16 v[14:17], v[142:145], v[216:219], v[14:17]
	s_setprio 0
	s_setprio 1
	v_mfma_f32_16x16x32_bf16 v[50:53], v[160:163], v[184:187], v[50:53]
	v_mfma_f32_16x16x32_bf16 v[42:45], v[168:171], v[184:187], v[42:45]
	v_mfma_f32_16x16x32_bf16 v[34:37], v[160:163], v[192:195], v[34:37]
	v_mfma_f32_16x16x32_bf16 v[26:29], v[168:171], v[192:195], v[26:29]
	v_mfma_f32_16x16x32_bf16 v[18:21], v[160:163], v[204:207], v[18:21]
	v_mfma_f32_16x16x32_bf16 v[10:13], v[168:171], v[204:207], v[10:13]
	v_mfma_f32_16x16x32_bf16 v[6:9], v[160:163], v[212:215], v[6:9]
	v_mfma_f32_16x16x32_bf16 v[2:5], v[168:171], v[212:215], v[2:5]
	v_mfma_f32_16x16x32_bf16 v[50:53], v[164:167], v[188:191], v[50:53]
	v_mfma_f32_16x16x32_bf16 v[42:45], v[180:183], v[188:191], v[42:45]
	v_mfma_f32_16x16x32_bf16 v[34:37], v[164:167], v[200:203], v[34:37]
	v_mfma_f32_16x16x32_bf16 v[26:29], v[180:183], v[200:203], v[26:29]
	v_mfma_f32_16x16x32_bf16 v[18:21], v[164:167], v[208:211], v[18:21]
	v_mfma_f32_16x16x32_bf16 v[10:13], v[180:183], v[208:211], v[10:13]
	v_mfma_f32_16x16x32_bf16 v[6:9], v[164:167], v[216:219], v[6:9]
	v_mfma_f32_16x16x32_bf16 v[2:5], v[180:183], v[216:219], v[2:5]
	s_setprio 0
	s_barrier
; #define PG8_STAGE(bufoff, gbase, voff) do { _Pragma("unroll") for (int _i = 0; _i < 2; ++_i) \
;         __builtin_amdgcn_global_load_lds((const unsigned*)((const char*)(gbase) + (voff)[_i]), (LAS unsigned*)(lds + (bufoff) + ldsw + _i * 8192), 16, 0, 0); } while (0)
; #define PG8_LDA(dst, b, h) do { _Pragma("unroll") for (int m = 0; m < 4; ++m) _Pragma("unroll") for (int k = 0; k < 2; ++k) dst[m][k] = *(const LAS bf16x8*)(lds + PG8_SA(b, h) + aoff + m * 2048 + k * 1024); } while (0)
; #define PG8_LDB(dst, b, h) do { _Pragma("unroll") for (int n = 0; n < 2; ++n) _Pragma("unroll") for (int k = 0; k < 2; ++k) dst[n][k] = *(const LAS bf16x8*)(lds + PG8_SB(b, h) + boff + n * 2048 + k * 1024); } while (0)
; #define PG8_MMA(ai, bj, At, Bt) do { __builtin_amdgcn_s_setprio(1); _Pragma("unroll") for (int m = 0; m < 4; ++m) _Pragma("unroll") for (int n = 0; n < 2; ++n) _Pragma("unroll") for (int k = 0; k < 2; ++k) \
;         acc[ai][bj][m][n] = __builtin_amdgcn_mfma_f32_16x16x32_bf16(Bt[n][k], At[m][k], acc[ai][bj][m][n], 0, 0, 0); __builtin_amdgcn_s_setprio(0); } while (0)
; #define PG8_WAIT_V(n) asm volatile("s_waitcnt vmcnt(" #n ")" ::: "memory")
; #define PG8_WAIT_L(n) asm volatile("s_waitcnt lgkmcnt(" #n ")" ::: "memory")
; #define PG8_BAR __builtin_amdgcn_s_barrier()
; #define PG8_SCHED __builtin_amdgcn_sched_barrier(0)
; template <class Epi, class Sched>
; __device__ __forceinline__ void gemm_phase(LAS unsigned char* lds, const int lda, const int ldb, const int K, const Sched& S, const Epi& E, int tid) {
;     ...
;             PG8_LDB(B0, 1, 0); PG8_LDB(B1, 1, 1); PG8_SCHED; PG8_LDA(At, 1, 0); PG8_STAGE(PG8_SA(0, 1), a2 + hA, voffA);
;             PG8_WAIT_V(8); PG8_WAIT_L(0); PG8_BAR; PG8_MMA(0, 0, At, B0); PG8_MMA(0, 1, At, B1); PG8_BAR; PG8_SCHED;
;             PG8_LDA(At, 1, 1); PG8_STAGE(PG8_SB(1, 0), b3, voffB); PG8_STAGE(PG8_SB(1, 1), b3 + hB, voffB); PG8_STAGE(PG8_SA(1, 0), a3, voffA);
;             PG8_WAIT_V(8); PG8_WAIT_L(0); PG8_BAR; PG8_MMA(1, 0, At, B0); PG8_MMA(1, 1, At, B1); PG8_BAR; PG8_SCHED;
;         }
;         if (wr == 0) PG8_BAR;
	s_add_i32 s22, 0, 0x18000
	v_add_u32_e32 v0, s22, v174
	s_add_i32 s23, 0, 0x1c000
	ds_read_b128 v[130:133], v0
	ds_read_b128 v[134:137], v0 offset:1024
	ds_read_b128 v[138:141], v0 offset:2048
	ds_read_b128 v[142:145], v0 offset:3072
	v_add_u32_e32 v0, s23, v174
	ds_read_b128 v[160:163], v0
	ds_read_b128 v[164:167], v0 offset:1024
	ds_read_b128 v[168:171], v0 offset:2048
	ds_read_b128 v[180:183], v0 offset:3072
	s_add_u32 s16, s16, 0x80000
	s_addc_u32 s17, s17, 0
	s_mov_b32 m0, s26
	ds_read_b128 v[184:187], v178 offset:32768
	ds_read_b128 v[188:191], v178 offset:33792
	ds_read_b128 v[192:195], v178 offset:34816
	ds_read_b128 v[200:203], v178 offset:35840
	ds_read_b128 v[204:207], v178 offset:36864
	ds_read_b128 v[208:211], v178 offset:37888
	ds_read_b128 v[212:215], v178 offset:38912
	ds_read_b128 v[216:219], v178 offset:39936
	global_load_lds_dwordx4 v146, s[16:17]
	s_mov_b32 m0, s27
	s_nop 0
	global_load_lds_dwordx4 v150, s[16:17]
	s_waitcnt vmcnt(8)
	s_waitcnt lgkmcnt(0)
	s_barrier
	s_setprio 1
	v_mfma_f32_16x16x32_bf16 v[126:129], v[130:133], v[184:187], v[126:129]
	v_mfma_f32_16x16x32_bf16 v[122:125], v[138:141], v[184:187], v[122:125]
	v_mfma_f32_16x16x32_bf16 v[118:121], v[130:133], v[192:195], v[118:121]
	v_mfma_f32_16x16x32_bf16 v[110:113], v[138:141], v[192:195], v[110:113]
	v_mfma_f32_16x16x32_bf16 v[102:105], v[130:133], v[204:207], v[102:105]
	v_mfma_f32_16x16x32_bf16 v[94:97], v[138:141], v[204:207], v[94:97]
	v_mfma_f32_16x16x32_bf16 v[86:89], v[130:133], v[212:215], v[86:89]
	v_mfma_f32_16x16x32_bf16 v[78:81], v[138:141], v[212:215], v[78:81]
	v_mfma_f32_16x16x32_bf16 v[126:129], v[134:137], v[188:191], v[126:129]
	v_mfma_f32_16x16x32_bf16 v[122:125], v[142:145], v[188:191], v[122:125]
	v_mfma_f32_16x16x32_bf16 v[118:121], v[134:137], v[200:203], v[118:121]
	v_mfma_f32_16x16x32_bf16 v[110:113], v[142:145], v[200:203], v[110:113]
	v_mfma_f32_16x16x32_bf16 v[102:105], v[134:137], v[208:211], v[102:105]
	v_mfma_f32_16x16x32_bf16 v[94:97], v[142:145], v[208:211], v[94:97]
	v_mfma_f32_16x16x32_bf16 v[86:89], v[134:137], v[216:219], v[86:89]
	v_mfma_f32_16x16x32_bf16 v[78:81], v[142:145], v[216:219], v[78:81]
	s_setprio 0
	s_setprio 1
	v_mfma_f32_16x16x32_bf16 v[114:117], v[160:163], v[184:187], v[114:117]
	v_mfma_f32_16x16x32_bf16 v[106:109], v[168:171], v[184:187], v[106:109]
	v_mfma_f32_16x16x32_bf16 v[98:101], v[160:163], v[192:195], v[98:101]
	v_mfma_f32_16x16x32_bf16 v[90:93], v[168:171], v[192:195], v[90:93]
	v_mfma_f32_16x16x32_bf16 v[82:85], v[160:163], v[204:207], v[82:85]
	v_mfma_f32_16x16x32_bf16 v[74:77], v[168:171], v[204:207], v[74:77]
	v_mfma_f32_16x16x32_bf16 v[70:73], v[160:163], v[212:215], v[70:73]
	v_mfma_f32_16x16x32_bf16 v[66:69], v[168:171], v[212:215], v[66:69]
	v_mfma_f32_16x16x32_bf16 v[114:117], v[164:167], v[188:191], v[114:117]
	v_mfma_f32_16x16x32_bf16 v[106:109], v[180:183], v[188:191], v[106:109]
	v_mfma_f32_16x16x32_bf16 v[98:101], v[164:167], v[200:203], v[98:101]
	v_mfma_f32_16x16x32_bf16 v[90:93], v[180:183], v[200:203], v[90:93]
	v_mfma_f32_16x16x32_bf16 v[82:85], v[164:167], v[208:211], v[82:85]
	v_mfma_f32_16x16x32_bf16 v[74:77], v[180:183], v[208:211], v[74:77]
	v_mfma_f32_16x16x32_bf16 v[70:73], v[164:167], v[216:219], v[70:73]
	v_mfma_f32_16x16x32_bf16 v[66:69], v[180:183], v[216:219], v[66:69]
	s_setprio 0
	s_barrier
	s_add_i32 s16, s22, s20
	s_mov_b32 m0, s16
	ds_read_b128 v[184:187], v178 offset:49152
	ds_read_b128 v[188:191], v178 offset:50176
	ds_read_b128 v[192:195], v178 offset:51200
	ds_read_b128 v[200:203], v178 offset:52224
	ds_read_b128 v[204:207], v178 offset:53248
	ds_read_b128 v[208:211], v178 offset:54272
	ds_read_b128 v[212:215], v178 offset:55296
	ds_read_b128 v[216:219], v178 offset:56320
	global_load_lds_dwordx4 v148, s[98:99]
	s_add_i32 m0, s16, 0x2000
	s_add_u32 s10, s10, 0x80080
	s_addc_u32 s11, s11, 0
	s_add_i32 s16, s23, s20
	global_load_lds_dwordx4 v152, s[98:99]
	s_mov_b32 m0, s16
	s_nop 0
	global_load_lds_dwordx4 v148, s[10:11]
	s_add_i32 m0, s16, 0x2000
	s_nop 0
	global_load_lds_dwordx4 v152, s[10:11]
	s_mov_b32 m0, s54
	s_nop 0
	global_load_lds_dwordx4 v146, s[100:101]
	s_mov_b32 m0, s55
	s_nop 0
	global_load_lds_dwordx4 v150, s[100:101]
	s_waitcnt vmcnt(8)
	s_waitcnt lgkmcnt(0)
	s_barrier
	s_setprio 1
	v_mfma_f32_16x16x32_bf16 v[62:65], v[130:133], v[184:187], v[62:65]
	v_mfma_f32_16x16x32_bf16 v[58:61], v[138:141], v[184:187], v[58:61]
	v_mfma_f32_16x16x32_bf16 v[54:57], v[130:133], v[192:195], v[54:57]
	v_mfma_f32_16x16x32_bf16 v[46:49], v[138:141], v[192:195], v[46:49]
	v_mfma_f32_16x16x32_bf16 v[38:41], v[130:133], v[204:207], v[38:41]
	v_mfma_f32_16x16x32_bf16 v[30:33], v[138:141], v[204:207], v[30:33]
	v_mfma_f32_16x16x32_bf16 v[22:25], v[130:133], v[212:215], v[22:25]
	v_mfma_f32_16x16x32_bf16 v[14:17], v[138:141], v[212:215], v[14:17]
	v_mfma_f32_16x16x32_bf16 v[62:65], v[134:137], v[188:191], v[62:65]
	v_mfma_f32_16x16x32_bf16 v[58:61], v[142:145], v[188:191], v[58:61]
	v_mfma_f32_16x16x32_bf16 v[54:57], v[134:137], v[200:203], v[54:57]
	v_mfma_f32_16x16x32_bf16 v[46:49], v[142:145], v[200:203], v[46:49]
	v_mfma_f32_16x16x32_bf16 v[38:41], v[134:137], v[208:211], v[38:41]
	v_mfma_f32_16x16x32_bf16 v[30:33], v[142:145], v[208:211], v[30:33]
	v_mfma_f32_16x16x32_bf16 v[22:25], v[134:137], v[216:219], v[22:25]
	v_mfma_f32_16x16x32_bf16 v[14:17], v[142:145], v[216:219], v[14:17]
	s_setprio 0
	s_setprio 1
	v_mfma_f32_16x16x32_bf16 v[50:53], v[160:163], v[184:187], v[50:53]
	v_mfma_f32_16x16x32_bf16 v[42:45], v[168:171], v[184:187], v[42:45]
	v_mfma_f32_16x16x32_bf16 v[34:37], v[160:163], v[192:195], v[34:37]
	v_mfma_f32_16x16x32_bf16 v[26:29], v[168:171], v[192:195], v[26:29]
	v_mfma_f32_16x16x32_bf16 v[18:21], v[160:163], v[204:207], v[18:21]
	v_mfma_f32_16x16x32_bf16 v[10:13], v[168:171], v[204:207], v[10:13]
	v_mfma_f32_16x16x32_bf16 v[6:9], v[160:163], v[212:215], v[6:9]
	v_mfma_f32_16x16x32_bf16 v[2:5], v[168:171], v[212:215], v[2:5]
	v_mfma_f32_16x16x32_bf16 v[50:53], v[164:167], v[188:191], v[50:53]
	v_mfma_f32_16x16x32_bf16 v[42:45], v[180:183], v[188:191], v[42:45]
	v_mfma_f32_16x16x32_bf16 v[34:37], v[164:167], v[200:203], v[34:37]
	v_mfma_f32_16x16x32_bf16 v[26:29], v[180:183], v[200:203], v[26:29]
	v_mfma_f32_16x16x32_bf16 v[18:21], v[164:167], v[208:211], v[18:21]
	v_mfma_f32_16x16x32_bf16 v[10:13], v[180:183], v[208:211], v[10:13]
	v_mfma_f32_16x16x32_bf16 v[6:9], v[164:167], v[216:219], v[6:9]
	v_mfma_f32_16x16x32_bf16 v[2:5], v[180:183], v[216:219], v[2:5]
	s_setprio 0
	s_barrier
	s_add_i32 s18, s18, 2
	s_add_u32 s4, s4, 0x100
	s_addc_u32 s5, s5, 0
	s_add_u32 s7, s7, 0x100
	s_addc_u32 s9, s9, 0
	s_cmp_gt_u32 s18, 29
	s_cbranch_scc0 .LBB0_91
	s_and_b64 vcc, exec, s[46:47]
	s_cbranch_vccz .LBB0_94
	s_barrier

; #define PG8_STAGE(bufoff, gbase, voff) do { _Pragma("unroll") for (int _i = 0; _i < 2; ++_i) \
;         __builtin_amdgcn_global_load_lds((const unsigned*)((const char*)(gbase) + (voff)[_i]), (LAS unsigned*)(lds + (bufoff) + ldsw + _i * 8192), 16, 0, 0); } while (0)
; #define PG8_LDA(dst, b, h) do { _Pragma("unroll") for (int m = 0; m < 4; ++m) _Pragma("unroll") for (int k = 0; k < 2; ++k) dst[m][k] = *(const LAS bf16x8*)(lds + PG8_SA(b, h) + aoff + m * 2048 + k * 1024); } while (0)
; #define PG8_LDB(dst, b, h) do { _Pragma("unroll") for (int n = 0; n < 2; ++n) _Pragma("unroll") for (int k = 0; k < 2; ++k) dst[n][k] = *(const LAS bf16x8*)(lds + PG8_SB(b, h) + boff + n * 2048 + k * 1024); } while (0)
; #define PG8_MMA(ai, bj, At, Bt) do { __builtin_amdgcn_s_setprio(1); _Pragma("unroll") for (int m = 0; m < 4; ++m) _Pragma("unroll") for (int n = 0; n < 2; ++n) _Pragma("unroll") for (int k = 0; k < 2; ++k) \
;         acc[ai][bj][m][n] = __builtin_amdgcn_mfma_f32_16x16x32_bf16(Bt[n][k], At[m][k], acc[ai][bj][m][n], 0, 0, 0); __builtin_amdgcn_s_setprio(0); } while (0)
; #define PG8_WAIT_V(n) asm volatile("s_waitcnt vmcnt(" #n ")" ::: "memory")
; #define PG8_WAIT_L(n) asm volatile("s_waitcnt lgkmcnt(" #n ")" ::: "memory")
; #define PG8_BAR __builtin_amdgcn_s_barrier()
; #define PG8_SCHED __builtin_amdgcn_sched_barrier(0)
; template <class Epi, class Sched>
; __device__ __forceinline__ void gemm_phase(LAS unsigned char* lds, const int lda, const int ldb, const int K, const Sched& S, const Epi& E, int tid) {
;     ...
;             const bool last = (t == nt - 2);
;             const char* a1 = cA + (size_t)(t + 1) * kstep;
;             const char* a2 = last ? nA : cA + (size_t)(t + 2) * kstep; const char* b2 = last ? nB : cB + (size_t)(t + 2) * kstep;
;             const char* a3 = a2 + kstep; const char* b3 = b2 + kstep;
;             PG8_LDB(B0, 0, 0); PG8_LDB(B1, 0, 1); PG8_SCHED; PG8_LDA(At, 0, 0); PG8_STAGE(PG8_SA(1, 1), a1 + hA, voffA);
;             PG8_WAIT_V(8); PG8_WAIT_L(0); PG8_BAR; PG8_MMA(0, 0, At, B0); PG8_MMA(0, 1, At, B1); PG8_BAR; PG8_SCHED;
;             PG8_LDA(At, 0, 1); PG8_STAGE(PG8_SB(0, 0), b2, voffB); PG8_STAGE(PG8_SB(0, 1), b2 + hB, voffB); PG8_STAGE(PG8_SA(0, 0), a2, voffA);
;             PG8_WAIT_V(8); PG8_WAIT_L(0); PG8_BAR; PG8_MMA(1, 0, At, B0); PG8_MMA(1, 1, At, B1); PG8_BAR; PG8_SCHED;
.LBB0_262:
	s_add_u32 s10, s8, 0xfff80080
	s_addc_u32 s11, s9, -1
	s_add_i32 s34, 0, 0x10000
	s_cmp_eq_u32 s43, 28
	s_cselect_b32 s15, s5, s11
	s_cselect_b32 s14, s4, s10
	s_cselect_b32 s11, s7, s42
	s_cselect_b32 s10, s6, s33
	s_add_i32 s35, 0, 0x14000
	v_add_u32_e32 v160, s34, v145
	v_add_u32_e32 v176, s35, v145
	ds_read_b128 v[148:151], v160
	ds_read_b128 v[152:155], v160 offset:1024
	ds_read_b128 v[156:159], v160 offset:2048
	ds_read_b128 v[160:163], v160 offset:3072
	ds_read_b128 v[164:167], v176
	ds_read_b128 v[168:171], v176 offset:1024
	ds_read_b128 v[172:175], v176 offset:2048
	ds_read_b128 v[176:179], v176 offset:3072
	s_add_i32 m0, s17, 0xc000
	ds_read_b128 v[180:183], v147
	ds_read_b128 v[184:187], v147 offset:1024
	ds_read_b128 v[188:191], v147 offset:2048
	ds_read_b128 v[192:195], v147 offset:3072
	ds_read_b128 v[200:203], v147 offset:4096
	ds_read_b128 v[204:207], v147 offset:5120
	ds_read_b128 v[208:211], v147 offset:6144
	ds_read_b128 v[212:215], v147 offset:7168
	global_load_lds_dwordx4 v140, s[8:9]
	s_add_i32 m0, s17, 0xe000
	s_nop 0
	global_load_lds_dwordx4 v142, s[8:9]
	s_waitcnt vmcnt(8)
	s_waitcnt lgkmcnt(0)
	s_barrier
	s_setprio 1
	v_mfma_f32_16x16x32_bf16 v[126:129], v[148:151], v[180:183], v[126:129]
	v_mfma_f32_16x16x32_bf16 v[122:125], v[156:159], v[180:183], v[122:125]
	v_mfma_f32_16x16x32_bf16 v[118:121], v[148:151], v[188:191], v[118:121]
	v_mfma_f32_16x16x32_bf16 v[114:117], v[156:159], v[188:191], v[114:117]
	v_mfma_f32_16x16x32_bf16 v[110:113], v[148:151], v[200:203], v[110:113]
	v_mfma_f32_16x16x32_bf16 v[102:105], v[156:159], v[200:203], v[102:105]
	v_mfma_f32_16x16x32_bf16 v[94:97], v[148:151], v[208:211], v[94:97]
	v_mfma_f32_16x16x32_bf16 v[86:89], v[156:159], v[208:211], v[86:89]
	v_mfma_f32_16x16x32_bf16 v[126:129], v[152:155], v[184:187], v[126:129]
	v_mfma_f32_16x16x32_bf16 v[122:125], v[160:163], v[184:187], v[122:125]
	v_mfma_f32_16x16x32_bf16 v[118:121], v[152:155], v[192:195], v[118:121]
	v_mfma_f32_16x16x32_bf16 v[114:117], v[160:163], v[192:195], v[114:117]
	v_mfma_f32_16x16x32_bf16 v[110:113], v[152:155], v[204:207], v[110:113]
	v_mfma_f32_16x16x32_bf16 v[102:105], v[160:163], v[204:207], v[102:105]
	v_mfma_f32_16x16x32_bf16 v[94:97], v[152:155], v[212:215], v[94:97]
	v_mfma_f32_16x16x32_bf16 v[86:89], v[160:163], v[212:215], v[86:89]
	s_setprio 0
	s_setprio 1
	v_mfma_f32_16x16x32_bf16 v[106:109], v[164:167], v[180:183], v[106:109]
	v_mfma_f32_16x16x32_bf16 v[98:101], v[172:175], v[180:183], v[98:101]
	v_mfma_f32_16x16x32_bf16 v[90:93], v[164:167], v[188:191], v[90:93]
	v_mfma_f32_16x16x32_bf16 v[82:85], v[172:175], v[188:191], v[82:85]
	v_mfma_f32_16x16x32_bf16 v[78:81], v[164:167], v[200:203], v[78:81]
	v_mfma_f32_16x16x32_bf16 v[74:77], v[172:175], v[200:203], v[74:77]
	v_mfma_f32_16x16x32_bf16 v[70:73], v[164:167], v[208:211], v[70:73]
	v_mfma_f32_16x16x32_bf16 v[66:69], v[172:175], v[208:211], v[66:69]
	v_mfma_f32_16x16x32_bf16 v[106:109], v[168:171], v[184:187], v[106:109]
	v_mfma_f32_16x16x32_bf16 v[98:101], v[176:179], v[184:187], v[98:101]
	v_mfma_f32_16x16x32_bf16 v[90:93], v[168:171], v[192:195], v[90:93]
	v_mfma_f32_16x16x32_bf16 v[82:85], v[176:179], v[192:195], v[82:85]
	v_mfma_f32_16x16x32_bf16 v[78:81], v[168:171], v[204:207], v[78:81]
	v_mfma_f32_16x16x32_bf16 v[74:77], v[176:179], v[204:207], v[74:77]
	v_mfma_f32_16x16x32_bf16 v[70:73], v[168:171], v[212:215], v[70:73]
	v_mfma_f32_16x16x32_bf16 v[66:69], v[176:179], v[212:215], v[66:69]
	s_setprio 0
	s_barrier
	s_add_u32 s98, s10, s30
	s_addc_u32 s99, s11, s31
	s_add_u32 s100, s14, s30
	s_addc_u32 s101, s15, s31
	s_add_i32 s34, s34, s16
	s_mov_b32 m0, s34
	ds_read_b128 v[180:183], v147 offset:16384
	ds_read_b128 v[184:187], v147 offset:17408
	ds_read_b128 v[188:191], v147 offset:18432
	ds_read_b128 v[192:195], v147 offset:19456
	ds_read_b128 v[200:203], v147 offset:20480
	ds_read_b128 v[204:207], v147 offset:21504
	ds_read_b128 v[208:211], v147 offset:22528
	ds_read_b128 v[212:215], v147 offset:23552
	global_load_lds_dwordx4 v132, s[10:11]
	s_add_i32 m0, s34, 0x2000
	s_add_u32 s44, s10, 0x80000
	s_addc_u32 s45, s11, 0
	s_add_i32 s34, s35, s16
	global_load_lds_dwordx4 v136, s[10:11]
	s_mov_b32 m0, s34
	s_nop 0
	global_load_lds_dwordx4 v132, s[44:45]
	s_add_i32 m0, s34, 0x2000
	s_nop 0
	global_load_lds_dwordx4 v136, s[44:45]
	s_mov_b32 m0, s17
	s_nop 0
	global_load_lds_dwordx4 v130, s[14:15]
	s_mov_b32 m0, s18
	s_nop 0
	global_load_lds_dwordx4 v134, s[14:15]
	s_waitcnt vmcnt(8)
	s_waitcnt lgkmcnt(0)
	s_barrier
	s_setprio 1
	v_mfma_f32_16x16x32_bf16 v[62:65], v[148:151], v[180:183], v[62:65]
	v_mfma_f32_16x16x32_bf16 v[58:61], v[156:159], v[180:183], v[58:61]
	v_mfma_f32_16x16x32_bf16 v[54:57], v[148:151], v[188:191], v[54:57]
	v_mfma_f32_16x16x32_bf16 v[50:53], v[156:159], v[188:191], v[50:53]
	v_mfma_f32_16x16x32_bf16 v[46:49], v[148:151], v[200:203], v[46:49]
	v_mfma_f32_16x16x32_bf16 v[38:41], v[156:159], v[200:203], v[38:41]
	v_mfma_f32_16x16x32_bf16 v[30:33], v[148:151], v[208:211], v[30:33]
	v_mfma_f32_16x16x32_bf16 v[22:25], v[156:159], v[208:211], v[22:25]
	v_mfma_f32_16x16x32_bf16 v[62:65], v[152:155], v[184:187], v[62:65]
	v_mfma_f32_16x16x32_bf16 v[58:61], v[160:163], v[184:187], v[58:61]
	v_mfma_f32_16x16x32_bf16 v[54:57], v[152:155], v[192:195], v[54:57]
	v_mfma_f32_16x16x32_bf16 v[50:53], v[160:163], v[192:195], v[50:53]
	v_mfma_f32_16x16x32_bf16 v[46:49], v[152:155], v[204:207], v[46:49]
	v_mfma_f32_16x16x32_bf16 v[38:41], v[160:163], v[204:207], v[38:41]
	v_mfma_f32_16x16x32_bf16 v[30:33], v[152:155], v[212:215], v[30:33]
	v_mfma_f32_16x16x32_bf16 v[22:25], v[160:163], v[212:215], v[22:25]
	s_setprio 0
	s_setprio 1
	v_mfma_f32_16x16x32_bf16 v[42:45], v[164:167], v[180:183], v[42:45]
	v_mfma_f32_16x16x32_bf16 v[34:37], v[172:175], v[180:183], v[34:37]
	v_mfma_f32_16x16x32_bf16 v[26:29], v[164:167], v[188:191], v[26:29]
	v_mfma_f32_16x16x32_bf16 v[18:21], v[172:175], v[188:191], v[18:21]
	v_mfma_f32_16x16x32_bf16 v[14:17], v[164:167], v[200:203], v[14:17]
	v_mfma_f32_16x16x32_bf16 v[10:13], v[172:175], v[200:203], v[10:13]
	v_mfma_f32_16x16x32_bf16 v[6:9], v[164:167], v[208:211], v[6:9]
	v_mfma_f32_16x16x32_bf16 v[2:5], v[172:175], v[208:211], v[2:5]
	v_mfma_f32_16x16x32_bf16 v[42:45], v[168:171], v[184:187], v[42:45]
	v_mfma_f32_16x16x32_bf16 v[34:37], v[176:179], v[184:187], v[34:37]
	v_mfma_f32_16x16x32_bf16 v[26:29], v[168:171], v[192:195], v[26:29]
	v_mfma_f32_16x16x32_bf16 v[18:21], v[176:179], v[192:195], v[18:21]
	v_mfma_f32_16x16x32_bf16 v[14:17], v[168:171], v[204:207], v[14:17]
	v_mfma_f32_16x16x32_bf16 v[10:13], v[176:179], v[204:207], v[10:13]
	v_mfma_f32_16x16x32_bf16 v[6:9], v[168:171], v[212:215], v[6:9]
	v_mfma_f32_16x16x32_bf16 v[2:5], v[176:179], v[212:215], v[2:5]
	s_setprio 0
	s_barrier
; #define PG8_STAGE(bufoff, gbase, voff) do { _Pragma("unroll") for (int _i = 0; _i < 2; ++_i) \
;         __builtin_amdgcn_global_load_lds((const unsigned*)((const char*)(gbase) + (voff)[_i]), (LAS unsigned*)(lds + (bufoff) + ldsw + _i * 8192), 16, 0, 0); } while (0)
; #define PG8_LDA(dst, b, h) do { _Pragma("unroll") for (int m = 0; m < 4; ++m) _Pragma("unroll") for (int k = 0; k < 2; ++k) dst[m][k] = *(const LAS bf16x8*)(lds + PG8_SA(b, h) + aoff + m * 2048 + k * 1024); } while (0)
; #define PG8_LDB(dst, b, h) do { _Pragma("unroll") for (int n = 0; n < 2; ++n) _Pragma("unroll") for (int k = 0; k < 2; ++k) dst[n][k] = *(const LAS bf16x8*)(lds + PG8_SB(b, h) + boff + n * 2048 + k * 1024); } while (0)
; #define PG8_MMA(ai, bj, At, Bt) do { __builtin_amdgcn_s_setprio(1); _Pragma("unroll") for (int m = 0; m < 4; ++m) _Pragma("unroll") for (int n = 0; n < 2; ++n) _Pragma("unroll") for (int k = 0; k < 2; ++k) \
;         acc[ai][bj][m][n] = __builtin_amdgcn_mfma_f32_16x16x32_bf16(Bt[n][k], At[m][k], acc[ai][bj][m][n], 0, 0, 0); __builtin_amdgcn_s_setprio(0); } while (0)
; #define PG8_WAIT_V(n) asm volatile("s_waitcnt vmcnt(" #n ")" ::: "memory")
; #define PG8_WAIT_L(n) asm volatile("s_waitcnt lgkmcnt(" #n ")" ::: "memory")
; #define PG8_BAR __builtin_amdgcn_s_barrier()
; #define PG8_SCHED __builtin_amdgcn_sched_barrier(0)
; template <class Epi, class Sched>
; __device__ __forceinline__ void gemm_phase(LAS unsigned char* lds, const int lda, const int ldb, const int K, const Sched& S, const Epi& E, int tid) {
;     ...
;             PG8_LDB(B0, 1, 0); PG8_LDB(B1, 1, 1); PG8_SCHED; PG8_LDA(At, 1, 0); PG8_STAGE(PG8_SA(0, 1), a2 + hA, voffA);
;             PG8_WAIT_V(8); PG8_WAIT_L(0); PG8_BAR; PG8_MMA(0, 0, At, B0); PG8_MMA(0, 1, At, B1); PG8_BAR; PG8_SCHED;
;             PG8_LDA(At, 1, 1); PG8_STAGE(PG8_SB(1, 0), b3, voffB); PG8_STAGE(PG8_SB(1, 1), b3 + hB, voffB); PG8_STAGE(PG8_SA(1, 0), a3, voffA);
;             PG8_WAIT_V(8); PG8_WAIT_L(0); PG8_BAR; PG8_MMA(1, 0, At, B0); PG8_MMA(1, 1, At, B1); PG8_BAR; PG8_SCHED;
;         }
;         if (wr == 0) PG8_BAR;
	s_add_i32 s34, 0, 0x18000
	s_add_i32 s35, 0, 0x1c000
	v_add_u32_e32 v160, s34, v145
	v_add_u32_e32 v176, s35, v145
	ds_read_b128 v[148:151], v160
	ds_read_b128 v[152:155], v160 offset:1024
	ds_read_b128 v[156:159], v160 offset:2048
	ds_read_b128 v[160:163], v160 offset:3072
	ds_read_b128 v[164:167], v176
	ds_read_b128 v[168:171], v176 offset:1024
	ds_read_b128 v[172:175], v176 offset:2048
	ds_read_b128 v[176:179], v176 offset:3072
	s_add_u32 s14, s14, 0x80000
	s_addc_u32 s15, s15, 0
	s_mov_b32 m0, s19
	ds_read_b128 v[180:183], v147 offset:32768
	ds_read_b128 v[184:187], v147 offset:33792
	ds_read_b128 v[188:191], v147 offset:34816
	ds_read_b128 v[192:195], v147 offset:35840
	ds_read_b128 v[200:203], v147 offset:36864
	ds_read_b128 v[204:207], v147 offset:37888
	ds_read_b128 v[208:211], v147 offset:38912
	ds_read_b128 v[212:215], v147 offset:39936
	global_load_lds_dwordx4 v130, s[14:15]
	s_mov_b32 m0, s20
	s_nop 0
	global_load_lds_dwordx4 v134, s[14:15]
	s_waitcnt vmcnt(8)
	s_waitcnt lgkmcnt(0)
	s_barrier
	s_setprio 1
	v_mfma_f32_16x16x32_bf16 v[126:129], v[148:151], v[180:183], v[126:129]
	v_mfma_f32_16x16x32_bf16 v[122:125], v[156:159], v[180:183], v[122:125]
	v_mfma_f32_16x16x32_bf16 v[118:121], v[148:151], v[188:191], v[118:121]
	v_mfma_f32_16x16x32_bf16 v[114:117], v[156:159], v[188:191], v[114:117]
	v_mfma_f32_16x16x32_bf16 v[110:113], v[148:151], v[200:203], v[110:113]
	v_mfma_f32_16x16x32_bf16 v[102:105], v[156:159], v[200:203], v[102:105]
	v_mfma_f32_16x16x32_bf16 v[94:97], v[148:151], v[208:211], v[94:97]
	v_mfma_f32_16x16x32_bf16 v[86:89], v[156:159], v[208:211], v[86:89]
	v_mfma_f32_16x16x32_bf16 v[126:129], v[152:155], v[184:187], v[126:129]
	v_mfma_f32_16x16x32_bf16 v[122:125], v[160:163], v[184:187], v[122:125]
	v_mfma_f32_16x16x32_bf16 v[118:121], v[152:155], v[192:195], v[118:121]
	v_mfma_f32_16x16x32_bf16 v[114:117], v[160:163], v[192:195], v[114:117]
	v_mfma_f32_16x16x32_bf16 v[110:113], v[152:155], v[204:207], v[110:113]
	v_mfma_f32_16x16x32_bf16 v[102:105], v[160:163], v[204:207], v[102:105]
	v_mfma_f32_16x16x32_bf16 v[94:97], v[152:155], v[212:215], v[94:97]
	v_mfma_f32_16x16x32_bf16 v[86:89], v[160:163], v[212:215], v[86:89]
	s_setprio 0
	s_setprio 1
	v_mfma_f32_16x16x32_bf16 v[106:109], v[164:167], v[180:183], v[106:109]
	v_mfma_f32_16x16x32_bf16 v[98:101], v[172:175], v[180:183], v[98:101]
	v_mfma_f32_16x16x32_bf16 v[90:93], v[164:167], v[188:191], v[90:93]
	v_mfma_f32_16x16x32_bf16 v[82:85], v[172:175], v[188:191], v[82:85]
	v_mfma_f32_16x16x32_bf16 v[78:81], v[164:167], v[200:203], v[78:81]
	v_mfma_f32_16x16x32_bf16 v[74:77], v[172:175], v[200:203], v[74:77]
	v_mfma_f32_16x16x32_bf16 v[70:73], v[164:167], v[208:211], v[70:73]
	v_mfma_f32_16x16x32_bf16 v[66:69], v[172:175], v[208:211], v[66:69]
	v_mfma_f32_16x16x32_bf16 v[106:109], v[168:171], v[184:187], v[106:109]
	v_mfma_f32_16x16x32_bf16 v[98:101], v[176:179], v[184:187], v[98:101]
	v_mfma_f32_16x16x32_bf16 v[90:93], v[168:171], v[192:195], v[90:93]
	v_mfma_f32_16x16x32_bf16 v[82:85], v[176:179], v[192:195], v[82:85]
	v_mfma_f32_16x16x32_bf16 v[78:81], v[168:171], v[204:207], v[78:81]
	v_mfma_f32_16x16x32_bf16 v[74:77], v[176:179], v[204:207], v[74:77]
	v_mfma_f32_16x16x32_bf16 v[70:73], v[168:171], v[212:215], v[70:73]
	v_mfma_f32_16x16x32_bf16 v[66:69], v[176:179], v[212:215], v[66:69]
	s_setprio 0
	s_barrier
	s_add_i32 s14, s34, s16
	s_mov_b32 m0, s14
	ds_read_b128 v[180:183], v147 offset:49152
	ds_read_b128 v[184:187], v147 offset:50176
	ds_read_b128 v[188:191], v147 offset:51200
	ds_read_b128 v[192:195], v147 offset:52224
	ds_read_b128 v[200:203], v147 offset:53248
	ds_read_b128 v[204:207], v147 offset:54272
	ds_read_b128 v[208:211], v147 offset:55296
	ds_read_b128 v[212:215], v147 offset:56320
	global_load_lds_dwordx4 v132, s[98:99]
	s_add_i32 m0, s14, 0x2000
	s_add_u32 s10, s10, 0x80080
	s_addc_u32 s11, s11, 0
	s_add_i32 s14, s35, s16
	global_load_lds_dwordx4 v136, s[98:99]
	s_mov_b32 m0, s14
	s_nop 0
	global_load_lds_dwordx4 v132, s[10:11]
	s_add_i32 m0, s14, 0x2000
	s_nop 0
	global_load_lds_dwordx4 v136, s[10:11]
	s_mov_b32 m0, s21
	s_nop 0
	global_load_lds_dwordx4 v130, s[100:101]
	s_mov_b32 m0, s22
	s_nop 0
	global_load_lds_dwordx4 v134, s[100:101]
	s_waitcnt vmcnt(8)
	s_waitcnt lgkmcnt(0)
	s_barrier
	s_setprio 1
	v_mfma_f32_16x16x32_bf16 v[62:65], v[148:151], v[180:183], v[62:65]
	v_mfma_f32_16x16x32_bf16 v[58:61], v[156:159], v[180:183], v[58:61]
	v_mfma_f32_16x16x32_bf16 v[54:57], v[148:151], v[188:191], v[54:57]
	v_mfma_f32_16x16x32_bf16 v[50:53], v[156:159], v[188:191], v[50:53]
	v_mfma_f32_16x16x32_bf16 v[46:49], v[148:151], v[200:203], v[46:49]
	v_mfma_f32_16x16x32_bf16 v[38:41], v[156:159], v[200:203], v[38:41]
	v_mfma_f32_16x16x32_bf16 v[30:33], v[148:151], v[208:211], v[30:33]
	v_mfma_f32_16x16x32_bf16 v[22:25], v[156:159], v[208:211], v[22:25]
	v_mfma_f32_16x16x32_bf16 v[62:65], v[152:155], v[184:187], v[62:65]
	v_mfma_f32_16x16x32_bf16 v[58:61], v[160:163], v[184:187], v[58:61]
	v_mfma_f32_16x16x32_bf16 v[54:57], v[152:155], v[192:195], v[54:57]
	v_mfma_f32_16x16x32_bf16 v[50:53], v[160:163], v[192:195], v[50:53]
	v_mfma_f32_16x16x32_bf16 v[46:49], v[152:155], v[204:207], v[46:49]
	v_mfma_f32_16x16x32_bf16 v[38:41], v[160:163], v[204:207], v[38:41]
	v_mfma_f32_16x16x32_bf16 v[30:33], v[152:155], v[212:215], v[30:33]
	v_mfma_f32_16x16x32_bf16 v[22:25], v[160:163], v[212:215], v[22:25]
	s_setprio 0
	s_setprio 1
	v_mfma_f32_16x16x32_bf16 v[42:45], v[164:167], v[180:183], v[42:45]
	v_mfma_f32_16x16x32_bf16 v[34:37], v[172:175], v[180:183], v[34:37]
	v_mfma_f32_16x16x32_bf16 v[26:29], v[164:167], v[188:191], v[26:29]
	v_mfma_f32_16x16x32_bf16 v[18:21], v[172:175], v[188:191], v[18:21]
	v_mfma_f32_16x16x32_bf16 v[14:17], v[164:167], v[200:203], v[14:17]
	v_mfma_f32_16x16x32_bf16 v[10:13], v[172:175], v[200:203], v[10:13]
	v_mfma_f32_16x16x32_bf16 v[6:9], v[164:167], v[208:211], v[6:9]
	v_mfma_f32_16x16x32_bf16 v[2:5], v[172:175], v[208:211], v[2:5]
	v_mfma_f32_16x16x32_bf16 v[42:45], v[168:171], v[184:187], v[42:45]
	v_mfma_f32_16x16x32_bf16 v[34:37], v[176:179], v[184:187], v[34:37]
	v_mfma_f32_16x16x32_bf16 v[26:29], v[168:171], v[192:195], v[26:29]
	v_mfma_f32_16x16x32_bf16 v[18:21], v[176:179], v[192:195], v[18:21]
	v_mfma_f32_16x16x32_bf16 v[14:17], v[168:171], v[204:207], v[14:17]
	v_mfma_f32_16x16x32_bf16 v[10:13], v[176:179], v[204:207], v[10:13]
	v_mfma_f32_16x16x32_bf16 v[6:9], v[168:171], v[212:215], v[6:9]
	v_mfma_f32_16x16x32_bf16 v[2:5], v[176:179], v[212:215], v[2:5]
	s_setprio 0
	s_barrier
	s_add_i32 s43, s43, 2
	s_add_u32 s8, s8, 0x100
	s_addc_u32 s9, s9, 0
	s_add_u32 s33, s33, 0x100
	s_addc_u32 s42, s42, 0
	s_cmp_gt_u32 s43, 29
	s_cbranch_scc0 .LBB0_262
	s_and_b64 vcc, exec, s[2:3]
	s_cbranch_vccz .LBB0_265
	s_barrier

; #define PG8_STAGE(bufoff, gbase, voff) do { _Pragma("unroll") for (int _i = 0; _i < 2; ++_i) \
;         __builtin_amdgcn_global_load_lds((const unsigned*)((const char*)(gbase) + (voff)[_i]), (LAS unsigned*)(lds + (bufoff) + ldsw + _i * 8192), 16, 0, 0); } while (0)
; #define PG8_LDA(dst, b, h) do { _Pragma("unroll") for (int m = 0; m < 4; ++m) _Pragma("unroll") for (int k = 0; k < 2; ++k) dst[m][k] = *(const LAS bf16x8*)(lds + PG8_SA(b, h) + aoff + m * 2048 + k * 1024); } while (0)
; #define PG8_LDB(dst, b, h) do { _Pragma("unroll") for (int n = 0; n < 2; ++n) _Pragma("unroll") for (int k = 0; k < 2; ++k) dst[n][k] = *(const LAS bf16x8*)(lds + PG8_SB(b, h) + boff + n * 2048 + k * 1024); } while (0)
; #define PG8_MMA(ai, bj, At, Bt) do { __builtin_amdgcn_s_setprio(1); _Pragma("unroll") for (int m = 0; m < 4; ++m) _Pragma("unroll") for (int n = 0; n < 2; ++n) _Pragma("unroll") for (int k = 0; k < 2; ++k) \
;         acc[ai][bj][m][n] = __builtin_amdgcn_mfma_f32_16x16x32_bf16(Bt[n][k], At[m][k], acc[ai][bj][m][n], 0, 0, 0); __builtin_amdgcn_s_setprio(0); } while (0)
; #define PG8_WAIT_V(n) asm volatile("s_waitcnt vmcnt(" #n ")" ::: "memory")
; #define PG8_WAIT_L(n) asm volatile("s_waitcnt lgkmcnt(" #n ")" ::: "memory")
; #define PG8_BAR __builtin_amdgcn_s_barrier()
; #define PG8_SCHED __builtin_amdgcn_sched_barrier(0)
; template <class Epi, class Sched>
; __device__ __forceinline__ void gemm_phase(LAS unsigned char* lds, const int lda, const int ldb, const int K, const Sched& S, const Epi& E, int tid) {
;     ...
;             const bool last = (t == nt - 2);
;             const char* a1 = cA + (size_t)(t + 1) * kstep;
;             const char* a2 = last ? nA : cA + (size_t)(t + 2) * kstep; const char* b2 = last ? nB : cB + (size_t)(t + 2) * kstep;
;             const char* a3 = a2 + kstep; const char* b3 = b2 + kstep;
;             PG8_LDB(B0, 0, 0); PG8_LDB(B1, 0, 1); PG8_SCHED; PG8_LDA(At, 0, 0); PG8_STAGE(PG8_SA(1, 1), a1 + hA, voffA);
;             PG8_WAIT_V(8); PG8_WAIT_L(0); PG8_BAR; PG8_MMA(0, 0, At, B0); PG8_MMA(0, 1, At, B1); PG8_BAR; PG8_SCHED;
;             PG8_LDA(At, 0, 1); PG8_STAGE(PG8_SB(0, 0), b2, voffB); PG8_STAGE(PG8_SB(0, 1), b2 + hB, voffB); PG8_STAGE(PG8_SA(0, 0), a2, voffA);
;             PG8_WAIT_V(8); PG8_WAIT_L(0); PG8_BAR; PG8_MMA(1, 0, At, B0); PG8_MMA(1, 1, At, B1); PG8_BAR; PG8_SCHED;
.LBB0_290:
	s_add_u32 s14, s10, 0xfff80080
	s_addc_u32 s15, s11, -1
	s_add_i32 s34, 0, 0x10000
	s_cmp_eq_u32 s42, 28
	s_cselect_b32 s17, s5, s15
	s_cselect_b32 s16, s4, s14
	s_cselect_b32 s15, s7, s33
	s_cselect_b32 s14, s6, s18
	s_add_i32 s35, 0, 0x14000
	v_add_u32_e32 v156, s34, v163
	v_add_u32_e32 v160, s35, v163
	ds_read_b128 v[144:147], v156
	ds_read_b128 v[148:151], v156 offset:1024
	ds_read_b128 v[152:155], v156 offset:2048
	ds_read_b128 v[156:159], v156 offset:3072
	ds_read_b128 v[166:169], v160
	ds_read_b128 v[170:173], v160 offset:1024
	ds_read_b128 v[174:177], v160 offset:2048
	ds_read_b128 v[178:181], v160 offset:3072
	s_add_i32 m0, s21, 0xc000
	ds_read_b128 v[182:185], v164
	ds_read_b128 v[186:189], v164 offset:1024
	ds_read_b128 v[190:193], v164 offset:2048
	ds_read_b128 v[194:197], v164 offset:3072
	ds_read_b128 v[200:203], v164 offset:4096
	ds_read_b128 v[204:207], v164 offset:5120
	ds_read_b128 v[208:211], v164 offset:6144
	ds_read_b128 v[212:215], v164 offset:7168
	global_load_lds_dwordx4 v140, s[10:11]
	s_add_i32 m0, s21, 0xe000
	s_nop 0
	global_load_lds_dwordx4 v142, s[10:11]
	s_waitcnt vmcnt(8)
	s_waitcnt lgkmcnt(0)
	s_barrier
	s_setprio 1
	v_mfma_f32_16x16x32_bf16 v[126:129], v[144:147], v[182:185], v[126:129]
	v_mfma_f32_16x16x32_bf16 v[122:125], v[152:155], v[182:185], v[122:125]
	v_mfma_f32_16x16x32_bf16 v[118:121], v[144:147], v[190:193], v[118:121]
	v_mfma_f32_16x16x32_bf16 v[114:117], v[152:155], v[190:193], v[114:117]
	v_mfma_f32_16x16x32_bf16 v[102:105], v[144:147], v[200:203], v[102:105]
	v_mfma_f32_16x16x32_bf16 v[98:101], v[152:155], v[200:203], v[98:101]
	v_mfma_f32_16x16x32_bf16 v[86:89], v[144:147], v[208:211], v[86:89]
	v_mfma_f32_16x16x32_bf16 v[82:85], v[152:155], v[208:211], v[82:85]
	v_mfma_f32_16x16x32_bf16 v[126:129], v[148:151], v[186:189], v[126:129]
	v_mfma_f32_16x16x32_bf16 v[122:125], v[156:159], v[186:189], v[122:125]
	v_mfma_f32_16x16x32_bf16 v[118:121], v[148:151], v[194:197], v[118:121]
	v_mfma_f32_16x16x32_bf16 v[114:117], v[156:159], v[194:197], v[114:117]
	v_mfma_f32_16x16x32_bf16 v[102:105], v[148:151], v[204:207], v[102:105]
	v_mfma_f32_16x16x32_bf16 v[98:101], v[156:159], v[204:207], v[98:101]
	v_mfma_f32_16x16x32_bf16 v[86:89], v[148:151], v[212:215], v[86:89]
	v_mfma_f32_16x16x32_bf16 v[82:85], v[156:159], v[212:215], v[82:85]
	s_setprio 0
	s_setprio 1
	v_mfma_f32_16x16x32_bf16 v[110:113], v[166:169], v[182:185], v[110:113]
	v_mfma_f32_16x16x32_bf16 v[106:109], v[174:177], v[182:185], v[106:109]
	v_mfma_f32_16x16x32_bf16 v[94:97], v[166:169], v[190:193], v[94:97]
	v_mfma_f32_16x16x32_bf16 v[90:93], v[174:177], v[190:193], v[90:93]
	v_mfma_f32_16x16x32_bf16 v[78:81], v[166:169], v[200:203], v[78:81]
	v_mfma_f32_16x16x32_bf16 v[74:77], v[174:177], v[200:203], v[74:77]
	v_mfma_f32_16x16x32_bf16 v[70:73], v[166:169], v[208:211], v[70:73]
	v_mfma_f32_16x16x32_bf16 v[66:69], v[174:177], v[208:211], v[66:69]
	v_mfma_f32_16x16x32_bf16 v[110:113], v[170:173], v[186:189], v[110:113]
	v_mfma_f32_16x16x32_bf16 v[106:109], v[178:181], v[186:189], v[106:109]
	v_mfma_f32_16x16x32_bf16 v[94:97], v[170:173], v[194:197], v[94:97]
	v_mfma_f32_16x16x32_bf16 v[90:93], v[178:181], v[194:197], v[90:93]
	v_mfma_f32_16x16x32_bf16 v[78:81], v[170:173], v[204:207], v[78:81]
	v_mfma_f32_16x16x32_bf16 v[74:77], v[178:181], v[204:207], v[74:77]
	v_mfma_f32_16x16x32_bf16 v[70:73], v[170:173], v[212:215], v[70:73]
	v_mfma_f32_16x16x32_bf16 v[66:69], v[178:181], v[212:215], v[66:69]
	s_setprio 0
	s_barrier
	s_add_u32 s98, s14, s30
	s_addc_u32 s99, s15, s31
	s_add_u32 s100, s16, s30
	s_addc_u32 s101, s17, s31
	s_add_i32 s34, s34, s20
	s_mov_b32 m0, s34
	ds_read_b128 v[182:185], v164 offset:16384
	ds_read_b128 v[186:189], v164 offset:17408
	ds_read_b128 v[190:193], v164 offset:18432
	ds_read_b128 v[194:197], v164 offset:19456
	ds_read_b128 v[200:203], v164 offset:20480
	ds_read_b128 v[204:207], v164 offset:21504
	ds_read_b128 v[208:211], v164 offset:22528
	ds_read_b128 v[212:215], v164 offset:23552
	global_load_lds_dwordx4 v0, s[14:15]
	s_add_i32 m0, s34, 0x2000
	s_add_u32 s44, s14, 0x80000
	s_addc_u32 s45, s15, 0
	s_add_i32 s34, s35, s20
	global_load_lds_dwordx4 v134, s[14:15]
	s_mov_b32 m0, s34
	s_nop 0
	global_load_lds_dwordx4 v0, s[44:45]
	s_add_i32 m0, s34, 0x2000
	s_nop 0
	global_load_lds_dwordx4 v134, s[44:45]
	s_mov_b32 m0, s21
	s_nop 0
	global_load_lds_dwordx4 v130, s[16:17]
	s_mov_b32 m0, s22
	s_nop 0
	global_load_lds_dwordx4 v132, s[16:17]
	s_waitcnt vmcnt(8)
	s_waitcnt lgkmcnt(0)
	s_barrier
	s_setprio 1
	v_mfma_f32_16x16x32_bf16 v[62:65], v[144:147], v[182:185], v[62:65]
	v_mfma_f32_16x16x32_bf16 v[58:61], v[152:155], v[182:185], v[58:61]
	v_mfma_f32_16x16x32_bf16 v[54:57], v[144:147], v[190:193], v[54:57]
	v_mfma_f32_16x16x32_bf16 v[50:53], v[152:155], v[190:193], v[50:53]
	v_mfma_f32_16x16x32_bf16 v[38:41], v[144:147], v[200:203], v[38:41]
	v_mfma_f32_16x16x32_bf16 v[34:37], v[152:155], v[200:203], v[34:37]
	v_mfma_f32_16x16x32_bf16 v[22:25], v[144:147], v[208:211], v[22:25]
	v_mfma_f32_16x16x32_bf16 v[18:21], v[152:155], v[208:211], v[18:21]
	v_mfma_f32_16x16x32_bf16 v[62:65], v[148:151], v[186:189], v[62:65]
	v_mfma_f32_16x16x32_bf16 v[58:61], v[156:159], v[186:189], v[58:61]
	v_mfma_f32_16x16x32_bf16 v[54:57], v[148:151], v[194:197], v[54:57]
	v_mfma_f32_16x16x32_bf16 v[50:53], v[156:159], v[194:197], v[50:53]
	v_mfma_f32_16x16x32_bf16 v[38:41], v[148:151], v[204:207], v[38:41]
	v_mfma_f32_16x16x32_bf16 v[34:37], v[156:159], v[204:207], v[34:37]
	v_mfma_f32_16x16x32_bf16 v[22:25], v[148:151], v[212:215], v[22:25]
	v_mfma_f32_16x16x32_bf16 v[18:21], v[156:159], v[212:215], v[18:21]
	s_setprio 0
	s_setprio 1
	v_mfma_f32_16x16x32_bf16 v[46:49], v[166:169], v[182:185], v[46:49]
	v_mfma_f32_16x16x32_bf16 v[42:45], v[174:177], v[182:185], v[42:45]
	v_mfma_f32_16x16x32_bf16 v[30:33], v[166:169], v[190:193], v[30:33]
	v_mfma_f32_16x16x32_bf16 v[26:29], v[174:177], v[190:193], v[26:29]
	v_mfma_f32_16x16x32_bf16 v[14:17], v[166:169], v[200:203], v[14:17]
	v_mfma_f32_16x16x32_bf16 v[10:13], v[174:177], v[200:203], v[10:13]
	v_mfma_f32_16x16x32_bf16 v[6:9], v[166:169], v[208:211], v[6:9]
	v_mfma_f32_16x16x32_bf16 v[2:5], v[174:177], v[208:211], v[2:5]
	v_mfma_f32_16x16x32_bf16 v[46:49], v[170:173], v[186:189], v[46:49]
	v_mfma_f32_16x16x32_bf16 v[42:45], v[178:181], v[186:189], v[42:45]
	v_mfma_f32_16x16x32_bf16 v[30:33], v[170:173], v[194:197], v[30:33]
	v_mfma_f32_16x16x32_bf16 v[26:29], v[178:181], v[194:197], v[26:29]
	v_mfma_f32_16x16x32_bf16 v[14:17], v[170:173], v[204:207], v[14:17]
	v_mfma_f32_16x16x32_bf16 v[10:13], v[178:181], v[204:207], v[10:13]
	v_mfma_f32_16x16x32_bf16 v[6:9], v[170:173], v[212:215], v[6:9]
	v_mfma_f32_16x16x32_bf16 v[2:5], v[178:181], v[212:215], v[2:5]
	s_setprio 0
	s_barrier
; #define PG8_STAGE(bufoff, gbase, voff) do { _Pragma("unroll") for (int _i = 0; _i < 2; ++_i) \
;         __builtin_amdgcn_global_load_lds((const unsigned*)((const char*)(gbase) + (voff)[_i]), (LAS unsigned*)(lds + (bufoff) + ldsw + _i * 8192), 16, 0, 0); } while (0)
; #define PG8_LDA(dst, b, h) do { _Pragma("unroll") for (int m = 0; m < 4; ++m) _Pragma("unroll") for (int k = 0; k < 2; ++k) dst[m][k] = *(const LAS bf16x8*)(lds + PG8_SA(b, h) + aoff + m * 2048 + k * 1024); } while (0)
; #define PG8_LDB(dst, b, h) do { _Pragma("unroll") for (int n = 0; n < 2; ++n) _Pragma("unroll") for (int k = 0; k < 2; ++k) dst[n][k] = *(const LAS bf16x8*)(lds + PG8_SB(b, h) + boff + n * 2048 + k * 1024); } while (0)
; #define PG8_MMA(ai, bj, At, Bt) do { __builtin_amdgcn_s_setprio(1); _Pragma("unroll") for (int m = 0; m < 4; ++m) _Pragma("unroll") for (int n = 0; n < 2; ++n) _Pragma("unroll") for (int k = 0; k < 2; ++k) \
;         acc[ai][bj][m][n] = __builtin_amdgcn_mfma_f32_16x16x32_bf16(Bt[n][k], At[m][k], acc[ai][bj][m][n], 0, 0, 0); __builtin_amdgcn_s_setprio(0); } while (0)
; #define PG8_WAIT_V(n) asm volatile("s_waitcnt vmcnt(" #n ")" ::: "memory")
; #define PG8_WAIT_L(n) asm volatile("s_waitcnt lgkmcnt(" #n ")" ::: "memory")
; #define PG8_BAR __builtin_amdgcn_s_barrier()
; #define PG8_SCHED __builtin_amdgcn_sched_barrier(0)
; template <class Epi, class Sched>
; __device__ __forceinline__ void gemm_phase(LAS unsigned char* lds, const int lda, const int ldb, const int K, const Sched& S, const Epi& E, int tid) {
;     ...
;             PG8_LDB(B0, 1, 0); PG8_LDB(B1, 1, 1); PG8_SCHED; PG8_LDA(At, 1, 0); PG8_STAGE(PG8_SA(0, 1), a2 + hA, voffA);
;             PG8_WAIT_V(8); PG8_WAIT_L(0); PG8_BAR; PG8_MMA(0, 0, At, B0); PG8_MMA(0, 1, At, B1); PG8_BAR; PG8_SCHED;
;             PG8_LDA(At, 1, 1); PG8_STAGE(PG8_SB(1, 0), b3, voffB); PG8_STAGE(PG8_SB(1, 1), b3 + hB, voffB); PG8_STAGE(PG8_SA(1, 0), a3, voffA);
;             PG8_WAIT_V(8); PG8_WAIT_L(0); PG8_BAR; PG8_MMA(1, 0, At, B0); PG8_MMA(1, 1, At, B1); PG8_BAR; PG8_SCHED;
;         }
;         if (wr == 0) PG8_BAR;
	s_add_i32 s34, 0, 0x18000
	s_add_i32 s35, 0, 0x1c000
	v_add_u32_e32 v156, s34, v163
	v_add_u32_e32 v165, s35, v163
	ds_read_b128 v[144:147], v156
	ds_read_b128 v[148:151], v156 offset:1024
	ds_read_b128 v[152:155], v156 offset:2048
	ds_read_b128 v[156:159], v156 offset:3072
	ds_read_b128 v[166:169], v165
	ds_read_b128 v[170:173], v165 offset:1024
	ds_read_b128 v[174:177], v165 offset:2048
	ds_read_b128 v[178:181], v165 offset:3072
	s_add_u32 s16, s16, 0x80000
	s_addc_u32 s17, s17, 0
	s_mov_b32 m0, s23
	ds_read_b128 v[182:185], v164 offset:32768
	ds_read_b128 v[186:189], v164 offset:33792
	ds_read_b128 v[190:193], v164 offset:34816
	ds_read_b128 v[194:197], v164 offset:35840
	ds_read_b128 v[200:203], v164 offset:36864
	ds_read_b128 v[204:207], v164 offset:37888
	ds_read_b128 v[208:211], v164 offset:38912
	ds_read_b128 v[212:215], v164 offset:39936
	global_load_lds_dwordx4 v130, s[16:17]
	s_mov_b32 m0, s25
	s_nop 0
	global_load_lds_dwordx4 v132, s[16:17]
	s_waitcnt vmcnt(8)
	s_waitcnt lgkmcnt(0)
	s_barrier
	s_setprio 1
	v_mfma_f32_16x16x32_bf16 v[126:129], v[144:147], v[182:185], v[126:129]
	v_mfma_f32_16x16x32_bf16 v[122:125], v[152:155], v[182:185], v[122:125]
	v_mfma_f32_16x16x32_bf16 v[118:121], v[144:147], v[190:193], v[118:121]
	v_mfma_f32_16x16x32_bf16 v[114:117], v[152:155], v[190:193], v[114:117]
	v_mfma_f32_16x16x32_bf16 v[102:105], v[144:147], v[200:203], v[102:105]
	v_mfma_f32_16x16x32_bf16 v[98:101], v[152:155], v[200:203], v[98:101]
	v_mfma_f32_16x16x32_bf16 v[86:89], v[144:147], v[208:211], v[86:89]
	v_mfma_f32_16x16x32_bf16 v[82:85], v[152:155], v[208:211], v[82:85]
	v_mfma_f32_16x16x32_bf16 v[126:129], v[148:151], v[186:189], v[126:129]
	v_mfma_f32_16x16x32_bf16 v[122:125], v[156:159], v[186:189], v[122:125]
	v_mfma_f32_16x16x32_bf16 v[118:121], v[148:151], v[194:197], v[118:121]
	v_mfma_f32_16x16x32_bf16 v[114:117], v[156:159], v[194:197], v[114:117]
	v_mfma_f32_16x16x32_bf16 v[102:105], v[148:151], v[204:207], v[102:105]
	v_mfma_f32_16x16x32_bf16 v[98:101], v[156:159], v[204:207], v[98:101]
	v_mfma_f32_16x16x32_bf16 v[86:89], v[148:151], v[212:215], v[86:89]
	v_mfma_f32_16x16x32_bf16 v[82:85], v[156:159], v[212:215], v[82:85]
	s_setprio 0
	s_setprio 1
	v_mfma_f32_16x16x32_bf16 v[110:113], v[166:169], v[182:185], v[110:113]
	v_mfma_f32_16x16x32_bf16 v[106:109], v[174:177], v[182:185], v[106:109]
	v_mfma_f32_16x16x32_bf16 v[94:97], v[166:169], v[190:193], v[94:97]
	v_mfma_f32_16x16x32_bf16 v[90:93], v[174:177], v[190:193], v[90:93]
	v_mfma_f32_16x16x32_bf16 v[78:81], v[166:169], v[200:203], v[78:81]
	v_mfma_f32_16x16x32_bf16 v[74:77], v[174:177], v[200:203], v[74:77]
	v_mfma_f32_16x16x32_bf16 v[70:73], v[166:169], v[208:211], v[70:73]
	v_mfma_f32_16x16x32_bf16 v[66:69], v[174:177], v[208:211], v[66:69]
	v_mfma_f32_16x16x32_bf16 v[110:113], v[170:173], v[186:189], v[110:113]
	v_mfma_f32_16x16x32_bf16 v[106:109], v[178:181], v[186:189], v[106:109]
	v_mfma_f32_16x16x32_bf16 v[94:97], v[170:173], v[194:197], v[94:97]
	v_mfma_f32_16x16x32_bf16 v[90:93], v[178:181], v[194:197], v[90:93]
	v_mfma_f32_16x16x32_bf16 v[78:81], v[170:173], v[204:207], v[78:81]
	v_mfma_f32_16x16x32_bf16 v[74:77], v[178:181], v[204:207], v[74:77]
	v_mfma_f32_16x16x32_bf16 v[70:73], v[170:173], v[212:215], v[70:73]
	v_mfma_f32_16x16x32_bf16 v[66:69], v[178:181], v[212:215], v[66:69]
	s_setprio 0
	s_barrier
	s_add_i32 s16, s34, s20
	s_mov_b32 m0, s16
	ds_read_b128 v[182:185], v164 offset:49152
	ds_read_b128 v[186:189], v164 offset:50176
	ds_read_b128 v[190:193], v164 offset:51200
	ds_read_b128 v[194:197], v164 offset:52224
	ds_read_b128 v[200:203], v164 offset:53248
	ds_read_b128 v[204:207], v164 offset:54272
	ds_read_b128 v[208:211], v164 offset:55296
	ds_read_b128 v[212:215], v164 offset:56320
	global_load_lds_dwordx4 v0, s[98:99]
	s_add_i32 m0, s16, 0x2000
	s_add_u32 s14, s14, 0x80080
	s_addc_u32 s15, s15, 0
	s_add_i32 s16, s35, s20
	global_load_lds_dwordx4 v134, s[98:99]
	s_mov_b32 m0, s16
	s_nop 0
	global_load_lds_dwordx4 v0, s[14:15]
	s_add_i32 m0, s16, 0x2000
	s_nop 0
	global_load_lds_dwordx4 v134, s[14:15]
	s_mov_b32 m0, s26
	s_nop 0
	global_load_lds_dwordx4 v130, s[100:101]
	s_mov_b32 m0, s27
	s_nop 0
	global_load_lds_dwordx4 v132, s[100:101]
	s_waitcnt vmcnt(8)
	s_waitcnt lgkmcnt(0)
	s_barrier
	s_setprio 1
	v_mfma_f32_16x16x32_bf16 v[62:65], v[144:147], v[182:185], v[62:65]
	v_mfma_f32_16x16x32_bf16 v[58:61], v[152:155], v[182:185], v[58:61]
	v_mfma_f32_16x16x32_bf16 v[54:57], v[144:147], v[190:193], v[54:57]
	v_mfma_f32_16x16x32_bf16 v[50:53], v[152:155], v[190:193], v[50:53]
	v_mfma_f32_16x16x32_bf16 v[38:41], v[144:147], v[200:203], v[38:41]
	v_mfma_f32_16x16x32_bf16 v[34:37], v[152:155], v[200:203], v[34:37]
	v_mfma_f32_16x16x32_bf16 v[22:25], v[144:147], v[208:211], v[22:25]
	v_mfma_f32_16x16x32_bf16 v[18:21], v[152:155], v[208:211], v[18:21]
	v_mfma_f32_16x16x32_bf16 v[62:65], v[148:151], v[186:189], v[62:65]
	v_mfma_f32_16x16x32_bf16 v[58:61], v[156:159], v[186:189], v[58:61]
	v_mfma_f32_16x16x32_bf16 v[54:57], v[148:151], v[194:197], v[54:57]
	v_mfma_f32_16x16x32_bf16 v[50:53], v[156:159], v[194:197], v[50:53]
	v_mfma_f32_16x16x32_bf16 v[38:41], v[148:151], v[204:207], v[38:41]
	v_mfma_f32_16x16x32_bf16 v[34:37], v[156:159], v[204:207], v[34:37]
	v_mfma_f32_16x16x32_bf16 v[22:25], v[148:151], v[212:215], v[22:25]
	v_mfma_f32_16x16x32_bf16 v[18:21], v[156:159], v[212:215], v[18:21]
	s_setprio 0
	s_setprio 1
	v_mfma_f32_16x16x32_bf16 v[46:49], v[166:169], v[182:185], v[46:49]
	v_mfma_f32_16x16x32_bf16 v[42:45], v[174:177], v[182:185], v[42:45]
	v_mfma_f32_16x16x32_bf16 v[30:33], v[166:169], v[190:193], v[30:33]
	v_mfma_f32_16x16x32_bf16 v[26:29], v[174:177], v[190:193], v[26:29]
	v_mfma_f32_16x16x32_bf16 v[14:17], v[166:169], v[200:203], v[14:17]
	v_mfma_f32_16x16x32_bf16 v[10:13], v[174:177], v[200:203], v[10:13]
	v_mfma_f32_16x16x32_bf16 v[6:9], v[166:169], v[208:211], v[6:9]
	v_mfma_f32_16x16x32_bf16 v[2:5], v[174:177], v[208:211], v[2:5]
	v_mfma_f32_16x16x32_bf16 v[46:49], v[170:173], v[186:189], v[46:49]
	v_mfma_f32_16x16x32_bf16 v[42:45], v[178:181], v[186:189], v[42:45]
	v_mfma_f32_16x16x32_bf16 v[30:33], v[170:173], v[194:197], v[30:33]
	v_mfma_f32_16x16x32_bf16 v[26:29], v[178:181], v[194:197], v[26:29]
	v_mfma_f32_16x16x32_bf16 v[14:17], v[170:173], v[204:207], v[14:17]
	v_mfma_f32_16x16x32_bf16 v[10:13], v[178:181], v[204:207], v[10:13]
	v_mfma_f32_16x16x32_bf16 v[6:9], v[170:173], v[212:215], v[6:9]
	v_mfma_f32_16x16x32_bf16 v[2:5], v[178:181], v[212:215], v[2:5]
	s_setprio 0
	s_barrier
	s_add_i32 s42, s42, 2
	s_add_u32 s10, s10, 0x100
	s_addc_u32 s11, s11, 0
	s_add_u32 s18, s18, 0x100
	s_addc_u32 s33, s33, 0
	s_cmp_gt_u32 s42, 29
	s_cbranch_scc0 .LBB0_290
	s_and_b64 vcc, exec, s[2:3]
	s_cbranch_vccz .LBB0_293
	s_barrier

; #define PG8_STAGE(bufoff, gbase, voff) do { _Pragma("unroll") for (int _i = 0; _i < 2; ++_i) \
;         __builtin_amdgcn_global_load_lds((const unsigned*)((const char*)(gbase) + (voff)[_i]), (LAS unsigned*)(lds + (bufoff) + ldsw + _i * 8192), 16, 0, 0); } while (0)
; #define PG8_LDA(dst, b, h) do { _Pragma("unroll") for (int m = 0; m < 4; ++m) _Pragma("unroll") for (int k = 0; k < 2; ++k) dst[m][k] = *(const LAS bf16x8*)(lds + PG8_SA(b, h) + aoff + m * 2048 + k * 1024); } while (0)
; #define PG8_LDB(dst, b, h) do { _Pragma("unroll") for (int n = 0; n < 2; ++n) _Pragma("unroll") for (int k = 0; k < 2; ++k) dst[n][k] = *(const LAS bf16x8*)(lds + PG8_SB(b, h) + boff + n * 2048 + k * 1024); } while (0)
; #define PG8_MMA(ai, bj, At, Bt) do { __builtin_amdgcn_s_setprio(1); _Pragma("unroll") for (int m = 0; m < 4; ++m) _Pragma("unroll") for (int n = 0; n < 2; ++n) _Pragma("unroll") for (int k = 0; k < 2; ++k) \
;         acc[ai][bj][m][n] = __builtin_amdgcn_mfma_f32_16x16x32_bf16(Bt[n][k], At[m][k], acc[ai][bj][m][n], 0, 0, 0); __builtin_amdgcn_s_setprio(0); } while (0)
; #define PG8_WAIT_V(n) asm volatile("s_waitcnt vmcnt(" #n ")" ::: "memory")
; #define PG8_WAIT_L(n) asm volatile("s_waitcnt lgkmcnt(" #n ")" ::: "memory")
; #define PG8_BAR __builtin_amdgcn_s_barrier()
; #define PG8_SCHED __builtin_amdgcn_sched_barrier(0)
; template <class Epi, class Sched>
; __device__ __forceinline__ void gemm_phase(LAS unsigned char* lds, const int lda, const int ldb, const int K, const Sched& S, const Epi& E, int tid) {
;     ...
;             const bool last = (t == nt - 2);
;             const char* a1 = cA + (size_t)(t + 1) * kstep;
;             const char* a2 = last ? nA : cA + (size_t)(t + 2) * kstep; const char* b2 = last ? nB : cB + (size_t)(t + 2) * kstep;
;             const char* a3 = a2 + kstep; const char* b3 = b2 + kstep;
;             PG8_LDB(B0, 0, 0); PG8_LDB(B1, 0, 1); PG8_SCHED; PG8_LDA(At, 0, 0); PG8_STAGE(PG8_SA(1, 1), a1 + hA, voffA);
;             PG8_WAIT_V(8); PG8_WAIT_L(0); PG8_BAR; PG8_MMA(0, 0, At, B0); PG8_MMA(0, 1, At, B1); PG8_BAR; PG8_SCHED;
;             PG8_LDA(At, 0, 1); PG8_STAGE(PG8_SB(0, 0), b2, voffB); PG8_STAGE(PG8_SB(0, 1), b2 + hB, voffB); PG8_STAGE(PG8_SA(0, 0), a2, voffA);
;             PG8_WAIT_V(8); PG8_WAIT_L(0); PG8_BAR; PG8_MMA(1, 0, At, B0); PG8_MMA(1, 1, At, B1); PG8_BAR; PG8_SCHED;
.LBB0_448:
	s_add_u32 s10, s8, 0x100
	s_addc_u32 s11, s9, 0
	s_add_i32 s34, 0, 0x10000
	s_cmp_eq_u32 s44, 2
	s_cselect_b32 s17, s5, s11
	s_cselect_b32 s16, s4, s10
	s_cselect_b32 s15, s7, s43
	s_cselect_b32 s14, s6, s42
	s_add_i32 s35, 0, 0x14000
	v_add_u32_e32 v152, s34, v157
	v_add_u32_e32 v172, s35, v157
	ds_read_b128 v[130:133], v152
	ds_read_b128 v[134:137], v152 offset:1024
	ds_read_b128 v[148:151], v152 offset:2048
	ds_read_b128 v[152:155], v152 offset:3072
	ds_read_b128 v[160:163], v172
	ds_read_b128 v[164:167], v172 offset:1024
	ds_read_b128 v[168:171], v172 offset:2048
	ds_read_b128 v[172:175], v172 offset:3072
	s_add_i32 m0, s19, 0xc000
	ds_read_b128 v[176:179], v159
	ds_read_b128 v[180:183], v159 offset:1024
	ds_read_b128 v[184:187], v159 offset:2048
	ds_read_b128 v[188:191], v159 offset:3072
	ds_read_b128 v[192:195], v159 offset:4096
	ds_read_b128 v[200:203], v159 offset:5120
	ds_read_b128 v[204:207], v159 offset:6144
	ds_read_b128 v[208:211], v159 offset:7168
	global_load_lds_dwordx4 v144, s[8:9]
	s_add_i32 m0, s19, 0xe000
	s_nop 0
	global_load_lds_dwordx4 v146, s[8:9]
	s_waitcnt vmcnt(8)
	s_waitcnt lgkmcnt(0)
	s_barrier
	s_setprio 1
	v_mfma_f32_16x16x32_bf16 v[126:129], v[130:133], v[176:179], v[126:129]
	v_mfma_f32_16x16x32_bf16 v[122:125], v[148:151], v[176:179], v[122:125]
	v_mfma_f32_16x16x32_bf16 v[118:121], v[130:133], v[184:187], v[118:121]
	v_mfma_f32_16x16x32_bf16 v[114:117], v[148:151], v[184:187], v[114:117]
	v_mfma_f32_16x16x32_bf16 v[110:113], v[130:133], v[192:195], v[110:113]
	v_mfma_f32_16x16x32_bf16 v[106:109], v[148:151], v[192:195], v[106:109]
	v_mfma_f32_16x16x32_bf16 v[102:105], v[130:133], v[204:207], v[102:105]
	v_mfma_f32_16x16x32_bf16 v[98:101], v[148:151], v[204:207], v[98:101]
	v_mfma_f32_16x16x32_bf16 v[126:129], v[134:137], v[180:183], v[126:129]
	v_mfma_f32_16x16x32_bf16 v[122:125], v[152:155], v[180:183], v[122:125]
	v_mfma_f32_16x16x32_bf16 v[118:121], v[134:137], v[188:191], v[118:121]
	v_mfma_f32_16x16x32_bf16 v[114:117], v[152:155], v[188:191], v[114:117]
	v_mfma_f32_16x16x32_bf16 v[110:113], v[134:137], v[200:203], v[110:113]
	v_mfma_f32_16x16x32_bf16 v[106:109], v[152:155], v[200:203], v[106:109]
	v_mfma_f32_16x16x32_bf16 v[102:105], v[134:137], v[208:211], v[102:105]
	v_mfma_f32_16x16x32_bf16 v[98:101], v[152:155], v[208:211], v[98:101]
	s_setprio 0
	s_setprio 1
	v_mfma_f32_16x16x32_bf16 v[74:77], v[160:163], v[176:179], v[74:77]
	v_mfma_f32_16x16x32_bf16 v[66:69], v[168:171], v[176:179], v[66:69]
	v_mfma_f32_16x16x32_bf16 v[54:57], v[160:163], v[184:187], v[54:57]
	v_mfma_f32_16x16x32_bf16 v[50:53], v[168:171], v[184:187], v[50:53]
	v_mfma_f32_16x16x32_bf16 v[46:49], v[160:163], v[192:195], v[46:49]
	v_mfma_f32_16x16x32_bf16 v[42:45], v[168:171], v[192:195], v[42:45]
	v_mfma_f32_16x16x32_bf16 v[38:41], v[160:163], v[204:207], v[38:41]
	v_mfma_f32_16x16x32_bf16 v[34:37], v[168:171], v[204:207], v[34:37]
	v_mfma_f32_16x16x32_bf16 v[74:77], v[164:167], v[180:183], v[74:77]
	v_mfma_f32_16x16x32_bf16 v[66:69], v[172:175], v[180:183], v[66:69]
	v_mfma_f32_16x16x32_bf16 v[54:57], v[164:167], v[188:191], v[54:57]
	v_mfma_f32_16x16x32_bf16 v[50:53], v[172:175], v[188:191], v[50:53]
	v_mfma_f32_16x16x32_bf16 v[46:49], v[164:167], v[200:203], v[46:49]
	v_mfma_f32_16x16x32_bf16 v[42:45], v[172:175], v[200:203], v[42:45]
	v_mfma_f32_16x16x32_bf16 v[38:41], v[164:167], v[208:211], v[38:41]
	v_mfma_f32_16x16x32_bf16 v[34:37], v[172:175], v[208:211], v[34:37]
	s_setprio 0
	s_barrier
	s_add_u32 s98, s14, s30
	s_addc_u32 s99, s15, s31
	s_add_u32 s100, s16, s30
	s_addc_u32 s101, s17, s31
	s_add_i32 s8, s34, s18
	s_mov_b32 m0, s8
	ds_read_b128 v[176:179], v159 offset:16384
	ds_read_b128 v[180:183], v159 offset:17408
	ds_read_b128 v[184:187], v159 offset:18432
	ds_read_b128 v[188:191], v159 offset:19456
	ds_read_b128 v[192:195], v159 offset:20480
	ds_read_b128 v[200:203], v159 offset:21504
	ds_read_b128 v[204:207], v159 offset:22528
	ds_read_b128 v[208:211], v159 offset:23552
	global_load_lds_dwordx4 v0, s[14:15]
	s_add_i32 m0, s8, 0x2000
	s_add_u32 s8, s14, 0x18000
	s_addc_u32 s9, s15, 0
	s_add_i32 s34, s35, s18
	global_load_lds_dwordx4 v142, s[14:15]
	s_mov_b32 m0, s34
	s_nop 0
	global_load_lds_dwordx4 v0, s[8:9]
	s_add_i32 m0, s34, 0x2000
	s_nop 0
	global_load_lds_dwordx4 v142, s[8:9]
	s_mov_b32 m0, s19
	s_nop 0
	global_load_lds_dwordx4 v138, s[16:17]
	s_mov_b32 m0, s20
	s_nop 0
	global_load_lds_dwordx4 v140, s[16:17]
	s_waitcnt vmcnt(8)
	s_waitcnt lgkmcnt(0)
	s_barrier
	s_setprio 1
	v_mfma_f32_16x16x32_bf16 v[94:97], v[130:133], v[176:179], v[94:97]
	v_mfma_f32_16x16x32_bf16 v[90:93], v[148:151], v[176:179], v[90:93]
	v_mfma_f32_16x16x32_bf16 v[86:89], v[130:133], v[184:187], v[86:89]
	v_mfma_f32_16x16x32_bf16 v[82:85], v[148:151], v[184:187], v[82:85]
	v_mfma_f32_16x16x32_bf16 v[78:81], v[130:133], v[192:195], v[78:81]
	v_mfma_f32_16x16x32_bf16 v[70:73], v[148:151], v[192:195], v[70:73]
	v_mfma_f32_16x16x32_bf16 v[62:65], v[130:133], v[204:207], v[62:65]
	v_mfma_f32_16x16x32_bf16 v[58:61], v[148:151], v[204:207], v[58:61]
	v_mfma_f32_16x16x32_bf16 v[94:97], v[134:137], v[180:183], v[94:97]
	v_mfma_f32_16x16x32_bf16 v[90:93], v[152:155], v[180:183], v[90:93]
	v_mfma_f32_16x16x32_bf16 v[86:89], v[134:137], v[188:191], v[86:89]
	v_mfma_f32_16x16x32_bf16 v[82:85], v[152:155], v[188:191], v[82:85]
	v_mfma_f32_16x16x32_bf16 v[78:81], v[134:137], v[200:203], v[78:81]
	v_mfma_f32_16x16x32_bf16 v[70:73], v[152:155], v[200:203], v[70:73]
	v_mfma_f32_16x16x32_bf16 v[62:65], v[134:137], v[208:211], v[62:65]
	v_mfma_f32_16x16x32_bf16 v[58:61], v[152:155], v[208:211], v[58:61]
	s_setprio 0
	s_setprio 1
	v_mfma_f32_16x16x32_bf16 v[30:33], v[160:163], v[176:179], v[30:33]
	v_mfma_f32_16x16x32_bf16 v[26:29], v[168:171], v[176:179], v[26:29]
	v_mfma_f32_16x16x32_bf16 v[22:25], v[160:163], v[184:187], v[22:25]
	v_mfma_f32_16x16x32_bf16 v[18:21], v[168:171], v[184:187], v[18:21]
	v_mfma_f32_16x16x32_bf16 v[14:17], v[160:163], v[192:195], v[14:17]
	v_mfma_f32_16x16x32_bf16 v[10:13], v[168:171], v[192:195], v[10:13]
	v_mfma_f32_16x16x32_bf16 v[6:9], v[160:163], v[204:207], v[6:9]
	v_mfma_f32_16x16x32_bf16 v[2:5], v[168:171], v[204:207], v[2:5]
	v_mfma_f32_16x16x32_bf16 v[30:33], v[164:167], v[180:183], v[30:33]
	v_mfma_f32_16x16x32_bf16 v[26:29], v[172:175], v[180:183], v[26:29]
	v_mfma_f32_16x16x32_bf16 v[22:25], v[164:167], v[188:191], v[22:25]
	v_mfma_f32_16x16x32_bf16 v[18:21], v[172:175], v[188:191], v[18:21]
	v_mfma_f32_16x16x32_bf16 v[14:17], v[164:167], v[200:203], v[14:17]
	v_mfma_f32_16x16x32_bf16 v[10:13], v[172:175], v[200:203], v[10:13]
	v_mfma_f32_16x16x32_bf16 v[6:9], v[164:167], v[208:211], v[6:9]
	v_mfma_f32_16x16x32_bf16 v[2:5], v[172:175], v[208:211], v[2:5]
	s_setprio 0
	s_barrier
; #define PG8_STAGE(bufoff, gbase, voff) do { _Pragma("unroll") for (int _i = 0; _i < 2; ++_i) \
;         __builtin_amdgcn_global_load_lds((const unsigned*)((const char*)(gbase) + (voff)[_i]), (LAS unsigned*)(lds + (bufoff) + ldsw + _i * 8192), 16, 0, 0); } while (0)
; #define PG8_LDA(dst, b, h) do { _Pragma("unroll") for (int m = 0; m < 4; ++m) _Pragma("unroll") for (int k = 0; k < 2; ++k) dst[m][k] = *(const LAS bf16x8*)(lds + PG8_SA(b, h) + aoff + m * 2048 + k * 1024); } while (0)
; #define PG8_LDB(dst, b, h) do { _Pragma("unroll") for (int n = 0; n < 2; ++n) _Pragma("unroll") for (int k = 0; k < 2; ++k) dst[n][k] = *(const LAS bf16x8*)(lds + PG8_SB(b, h) + boff + n * 2048 + k * 1024); } while (0)
; #define PG8_MMA(ai, bj, At, Bt) do { __builtin_amdgcn_s_setprio(1); _Pragma("unroll") for (int m = 0; m < 4; ++m) _Pragma("unroll") for (int n = 0; n < 2; ++n) _Pragma("unroll") for (int k = 0; k < 2; ++k) \
;         acc[ai][bj][m][n] = __builtin_amdgcn_mfma_f32_16x16x32_bf16(Bt[n][k], At[m][k], acc[ai][bj][m][n], 0, 0, 0); __builtin_amdgcn_s_setprio(0); } while (0)
; #define PG8_WAIT_V(n) asm volatile("s_waitcnt vmcnt(" #n ")" ::: "memory")
; #define PG8_WAIT_L(n) asm volatile("s_waitcnt lgkmcnt(" #n ")" ::: "memory")
; #define PG8_BAR __builtin_amdgcn_s_barrier()
; #define PG8_SCHED __builtin_amdgcn_sched_barrier(0)
; template <class Epi, class Sched>
; __device__ __forceinline__ void gemm_phase(LAS unsigned char* lds, const int lda, const int ldb, const int K, const Sched& S, const Epi& E, int tid) {
;     ...
;             PG8_LDB(B0, 1, 0); PG8_LDB(B1, 1, 1); PG8_SCHED; PG8_LDA(At, 1, 0); PG8_STAGE(PG8_SA(0, 1), a2 + hA, voffA);
;             PG8_WAIT_V(8); PG8_WAIT_L(0); PG8_BAR; PG8_MMA(0, 0, At, B0); PG8_MMA(0, 1, At, B1); PG8_BAR; PG8_SCHED;
;             PG8_LDA(At, 1, 1); PG8_STAGE(PG8_SB(1, 0), b3, voffB); PG8_STAGE(PG8_SB(1, 1), b3 + hB, voffB); PG8_STAGE(PG8_SA(1, 0), a3, voffA);
;             PG8_WAIT_V(8); PG8_WAIT_L(0); PG8_BAR; PG8_MMA(1, 0, At, B0); PG8_MMA(1, 1, At, B1); PG8_BAR; PG8_SCHED;
;         }
;         if (wr == 0) PG8_BAR;
	s_add_i32 s34, 0, 0x18000
	s_add_i32 s35, 0, 0x1c000
	v_add_u32_e32 v152, s34, v157
	v_add_u32_e32 v172, s35, v157
	ds_read_b128 v[130:133], v152
	ds_read_b128 v[134:137], v152 offset:1024
	ds_read_b128 v[148:151], v152 offset:2048
	ds_read_b128 v[152:155], v152 offset:3072
	ds_read_b128 v[160:163], v172
	ds_read_b128 v[164:167], v172 offset:1024
	ds_read_b128 v[168:171], v172 offset:2048
	ds_read_b128 v[172:175], v172 offset:3072
	s_add_u32 s8, s16, 0x60000
	s_addc_u32 s9, s17, 0
	s_mov_b32 m0, s21
	ds_read_b128 v[176:179], v159 offset:32768
	ds_read_b128 v[180:183], v159 offset:33792
	ds_read_b128 v[184:187], v159 offset:34816
	ds_read_b128 v[188:191], v159 offset:35840
	ds_read_b128 v[192:195], v159 offset:36864
	ds_read_b128 v[200:203], v159 offset:37888
	ds_read_b128 v[204:207], v159 offset:38912
	ds_read_b128 v[208:211], v159 offset:39936
	global_load_lds_dwordx4 v138, s[8:9]
	s_mov_b32 m0, s22
	s_nop 0
	global_load_lds_dwordx4 v140, s[8:9]
	s_waitcnt vmcnt(8)
	s_waitcnt lgkmcnt(0)
	s_barrier
	s_setprio 1
	v_mfma_f32_16x16x32_bf16 v[126:129], v[130:133], v[176:179], v[126:129]
	v_mfma_f32_16x16x32_bf16 v[122:125], v[148:151], v[176:179], v[122:125]
	v_mfma_f32_16x16x32_bf16 v[118:121], v[130:133], v[184:187], v[118:121]
	v_mfma_f32_16x16x32_bf16 v[114:117], v[148:151], v[184:187], v[114:117]
	v_mfma_f32_16x16x32_bf16 v[110:113], v[130:133], v[192:195], v[110:113]
	v_mfma_f32_16x16x32_bf16 v[106:109], v[148:151], v[192:195], v[106:109]
	v_mfma_f32_16x16x32_bf16 v[102:105], v[130:133], v[204:207], v[102:105]
	v_mfma_f32_16x16x32_bf16 v[98:101], v[148:151], v[204:207], v[98:101]
	v_mfma_f32_16x16x32_bf16 v[126:129], v[134:137], v[180:183], v[126:129]
	v_mfma_f32_16x16x32_bf16 v[122:125], v[152:155], v[180:183], v[122:125]
	v_mfma_f32_16x16x32_bf16 v[118:121], v[134:137], v[188:191], v[118:121]
	v_mfma_f32_16x16x32_bf16 v[114:117], v[152:155], v[188:191], v[114:117]
	v_mfma_f32_16x16x32_bf16 v[110:113], v[134:137], v[200:203], v[110:113]
	v_mfma_f32_16x16x32_bf16 v[106:109], v[152:155], v[200:203], v[106:109]
	v_mfma_f32_16x16x32_bf16 v[102:105], v[134:137], v[208:211], v[102:105]
	v_mfma_f32_16x16x32_bf16 v[98:101], v[152:155], v[208:211], v[98:101]
	s_setprio 0
	s_setprio 1
	v_mfma_f32_16x16x32_bf16 v[74:77], v[160:163], v[176:179], v[74:77]
	v_mfma_f32_16x16x32_bf16 v[66:69], v[168:171], v[176:179], v[66:69]
	v_mfma_f32_16x16x32_bf16 v[54:57], v[160:163], v[184:187], v[54:57]
	v_mfma_f32_16x16x32_bf16 v[50:53], v[168:171], v[184:187], v[50:53]
	v_mfma_f32_16x16x32_bf16 v[46:49], v[160:163], v[192:195], v[46:49]
	v_mfma_f32_16x16x32_bf16 v[42:45], v[168:171], v[192:195], v[42:45]
	v_mfma_f32_16x16x32_bf16 v[38:41], v[160:163], v[204:207], v[38:41]
	v_mfma_f32_16x16x32_bf16 v[34:37], v[168:171], v[204:207], v[34:37]
	v_mfma_f32_16x16x32_bf16 v[74:77], v[164:167], v[180:183], v[74:77]
	v_mfma_f32_16x16x32_bf16 v[66:69], v[172:175], v[180:183], v[66:69]
	v_mfma_f32_16x16x32_bf16 v[54:57], v[164:167], v[188:191], v[54:57]
	v_mfma_f32_16x16x32_bf16 v[50:53], v[172:175], v[188:191], v[50:53]
	v_mfma_f32_16x16x32_bf16 v[46:49], v[164:167], v[200:203], v[46:49]
	v_mfma_f32_16x16x32_bf16 v[42:45], v[172:175], v[200:203], v[42:45]
	v_mfma_f32_16x16x32_bf16 v[38:41], v[164:167], v[208:211], v[38:41]
	v_mfma_f32_16x16x32_bf16 v[34:37], v[172:175], v[208:211], v[34:37]
	s_setprio 0
	s_barrier
	s_add_i32 s8, s34, s18
	s_mov_b32 m0, s8
	ds_read_b128 v[176:179], v159 offset:49152
	ds_read_b128 v[180:183], v159 offset:50176
	ds_read_b128 v[184:187], v159 offset:51200
	ds_read_b128 v[188:191], v159 offset:52224
	ds_read_b128 v[192:195], v159 offset:53248
	ds_read_b128 v[200:203], v159 offset:54272
	ds_read_b128 v[204:207], v159 offset:55296
	ds_read_b128 v[208:211], v159 offset:56320
	global_load_lds_dwordx4 v0, s[98:99]
	s_add_i32 m0, s8, 0x2000
	s_add_u32 s8, s14, 0x18080
	s_addc_u32 s9, s15, 0
	s_add_i32 s14, s35, s18
	global_load_lds_dwordx4 v142, s[98:99]
	s_mov_b32 m0, s14
	s_nop 0
	global_load_lds_dwordx4 v0, s[8:9]
	s_add_i32 m0, s14, 0x2000
	s_nop 0
	global_load_lds_dwordx4 v142, s[8:9]
	s_mov_b32 m0, s23
	s_nop 0
	global_load_lds_dwordx4 v138, s[100:101]
	s_mov_b32 m0, s25
	s_nop 0
	global_load_lds_dwordx4 v140, s[100:101]
	s_waitcnt vmcnt(8)
	s_waitcnt lgkmcnt(0)
	s_barrier
	s_setprio 1
	v_mfma_f32_16x16x32_bf16 v[94:97], v[130:133], v[176:179], v[94:97]
	v_mfma_f32_16x16x32_bf16 v[90:93], v[148:151], v[176:179], v[90:93]
	v_mfma_f32_16x16x32_bf16 v[86:89], v[130:133], v[184:187], v[86:89]
	v_mfma_f32_16x16x32_bf16 v[82:85], v[148:151], v[184:187], v[82:85]
	v_mfma_f32_16x16x32_bf16 v[78:81], v[130:133], v[192:195], v[78:81]
	v_mfma_f32_16x16x32_bf16 v[70:73], v[148:151], v[192:195], v[70:73]
	v_mfma_f32_16x16x32_bf16 v[62:65], v[130:133], v[204:207], v[62:65]
	v_mfma_f32_16x16x32_bf16 v[58:61], v[148:151], v[204:207], v[58:61]
	v_mfma_f32_16x16x32_bf16 v[94:97], v[134:137], v[180:183], v[94:97]
	v_mfma_f32_16x16x32_bf16 v[90:93], v[152:155], v[180:183], v[90:93]
	v_mfma_f32_16x16x32_bf16 v[86:89], v[134:137], v[188:191], v[86:89]
	v_mfma_f32_16x16x32_bf16 v[82:85], v[152:155], v[188:191], v[82:85]
	v_mfma_f32_16x16x32_bf16 v[78:81], v[134:137], v[200:203], v[78:81]
	v_mfma_f32_16x16x32_bf16 v[70:73], v[152:155], v[200:203], v[70:73]
	v_mfma_f32_16x16x32_bf16 v[62:65], v[134:137], v[208:211], v[62:65]
	v_mfma_f32_16x16x32_bf16 v[58:61], v[152:155], v[208:211], v[58:61]
	s_setprio 0
	s_setprio 1
	v_mfma_f32_16x16x32_bf16 v[30:33], v[160:163], v[176:179], v[30:33]
	v_mfma_f32_16x16x32_bf16 v[26:29], v[168:171], v[176:179], v[26:29]
	v_mfma_f32_16x16x32_bf16 v[22:25], v[160:163], v[184:187], v[22:25]
	v_mfma_f32_16x16x32_bf16 v[18:21], v[168:171], v[184:187], v[18:21]
	v_mfma_f32_16x16x32_bf16 v[14:17], v[160:163], v[192:195], v[14:17]
	v_mfma_f32_16x16x32_bf16 v[10:13], v[168:171], v[192:195], v[10:13]
	v_mfma_f32_16x16x32_bf16 v[6:9], v[160:163], v[204:207], v[6:9]
	v_mfma_f32_16x16x32_bf16 v[2:5], v[168:171], v[204:207], v[2:5]
	v_mfma_f32_16x16x32_bf16 v[30:33], v[164:167], v[180:183], v[30:33]
	v_mfma_f32_16x16x32_bf16 v[26:29], v[172:175], v[180:183], v[26:29]
	v_mfma_f32_16x16x32_bf16 v[22:25], v[164:167], v[188:191], v[22:25]
	v_mfma_f32_16x16x32_bf16 v[18:21], v[172:175], v[188:191], v[18:21]
	v_mfma_f32_16x16x32_bf16 v[14:17], v[164:167], v[200:203], v[14:17]
	v_mfma_f32_16x16x32_bf16 v[10:13], v[172:175], v[200:203], v[10:13]
	v_mfma_f32_16x16x32_bf16 v[6:9], v[164:167], v[208:211], v[6:9]
	v_mfma_f32_16x16x32_bf16 v[2:5], v[172:175], v[208:211], v[2:5]
	s_setprio 0
	s_barrier
	s_add_i32 s44, s44, 2
	s_add_u32 s42, s42, 0x100
	s_addc_u32 s43, s43, 0
	s_cmp_gt_u32 s44, 3
	s_mov_b64 s[8:9], s[10:11]
	s_cbranch_scc0 .LBB0_448
	s_and_b64 vcc, exec, s[2:3]
	s_cbranch_vccz .LBB0_451
	s_barrier

; #define PG8_STAGE(bufoff, gbase, voff) do { _Pragma("unroll") for (int _i = 0; _i < 2; ++_i) \
;         __builtin_amdgcn_global_load_lds((const unsigned*)((const char*)(gbase) + (voff)[_i]), (LAS unsigned*)(lds + (bufoff) + ldsw + _i * 8192), 16, 0, 0); } while (0)
; #define PG8_LDA(dst, b, h) do { _Pragma("unroll") for (int m = 0; m < 4; ++m) _Pragma("unroll") for (int k = 0; k < 2; ++k) dst[m][k] = *(const LAS bf16x8*)(lds + PG8_SA(b, h) + aoff + m * 2048 + k * 1024); } while (0)
; #define PG8_LDB(dst, b, h) do { _Pragma("unroll") for (int n = 0; n < 2; ++n) _Pragma("unroll") for (int k = 0; k < 2; ++k) dst[n][k] = *(const LAS bf16x8*)(lds + PG8_SB(b, h) + boff + n * 2048 + k * 1024); } while (0)
; #define PG8_MMA(ai, bj, At, Bt) do { __builtin_amdgcn_s_setprio(1); _Pragma("unroll") for (int m = 0; m < 4; ++m) _Pragma("unroll") for (int n = 0; n < 2; ++n) _Pragma("unroll") for (int k = 0; k < 2; ++k) \
;         acc[ai][bj][m][n] = __builtin_amdgcn_mfma_f32_16x16x32_bf16(Bt[n][k], At[m][k], acc[ai][bj][m][n], 0, 0, 0); __builtin_amdgcn_s_setprio(0); } while (0)
; #define PG8_WAIT_V(n) asm volatile("s_waitcnt vmcnt(" #n ")" ::: "memory")
; #define PG8_WAIT_L(n) asm volatile("s_waitcnt lgkmcnt(" #n ")" ::: "memory")
; #define PG8_BAR __builtin_amdgcn_s_barrier()
; #define PG8_SCHED __builtin_amdgcn_sched_barrier(0)
; template <class Epi, class Sched>
; __device__ __forceinline__ void gemm_phase(LAS unsigned char* lds, const int lda, const int ldb, const int K, const Sched& S, const Epi& E, int tid) {
;     ...
;             const bool last = (t == nt - 2);
;             const char* a1 = cA + (size_t)(t + 1) * kstep;
;             const char* a2 = last ? nA : cA + (size_t)(t + 2) * kstep; const char* b2 = last ? nB : cB + (size_t)(t + 2) * kstep;
;             const char* a3 = a2 + kstep; const char* b3 = b2 + kstep;
;             PG8_LDB(B0, 0, 0); PG8_LDB(B1, 0, 1); PG8_SCHED; PG8_LDA(At, 0, 0); PG8_STAGE(PG8_SA(1, 1), a1 + hA, voffA);
;             PG8_WAIT_V(8); PG8_WAIT_L(0); PG8_BAR; PG8_MMA(0, 0, At, B0); PG8_MMA(0, 1, At, B1); PG8_BAR; PG8_SCHED;
;             PG8_LDA(At, 0, 1); PG8_STAGE(PG8_SB(0, 0), b2, voffB); PG8_STAGE(PG8_SB(0, 1), b2 + hB, voffB); PG8_STAGE(PG8_SA(0, 0), a2, voffA);
;             PG8_WAIT_V(8); PG8_WAIT_L(0); PG8_BAR; PG8_MMA(1, 0, At, B0); PG8_MMA(1, 1, At, B1); PG8_BAR; PG8_SCHED;
.LBB0_530:
	s_add_u32 s8, s6, 0xfff80080
	s_addc_u32 s9, s7, -1
	s_add_i32 s16, 0, 0x10000
	s_cmp_eq_u32 s15, 28
	s_cselect_b32 s11, s53, s9
	s_cselect_b32 s10, s52, s8
	v_add_u32_e32 v106, s16, v208
	s_cselect_b32 s9, s55, s14
	s_cselect_b32 s8, s54, s3
	s_add_i32 s22, 0, 0x14000
	ds_read_b128 v[102:105], v106
	ds_read_b128 v[128:131], v106 offset:1024
	ds_read_b128 v[132:135], v106 offset:2048
	ds_read_b128 v[154:157], v106 offset:3072
	v_add_u32_e32 v106, s22, v208
	ds_read_b128 v[158:161], v106
	ds_read_b128 v[162:165], v106 offset:1024
	ds_read_b128 v[166:169], v106 offset:2048
	ds_read_b128 v[170:173], v106 offset:3072
	s_add_i32 m0, s20, 0xc000
	ds_read_b128 v[174:177], v210
	ds_read_b128 v[178:181], v210 offset:1024
	ds_read_b128 v[182:185], v210 offset:2048
	ds_read_b128 v[186:189], v210 offset:3072
	ds_read_b128 v[190:193], v210 offset:4096
	ds_read_b128 v[194:197], v210 offset:5120
	ds_read_b128 v[200:203], v210 offset:6144
	ds_read_b128 v[204:207], v210 offset:7168
	global_load_lds_dwordx4 v150, s[6:7]
	s_add_i32 m0, s20, 0xe000
	s_nop 0
	global_load_lds_dwordx4 v152, s[6:7]
	s_waitcnt vmcnt(8)
	s_waitcnt lgkmcnt(0)
	s_barrier
	s_setprio 1
	v_mfma_f32_16x16x32_bf16 v[140:143], v[102:105], v[174:177], v[140:143]
	v_mfma_f32_16x16x32_bf16 v[94:97], v[132:135], v[174:177], v[94:97]
	v_mfma_f32_16x16x32_bf16 v[136:139], v[102:105], v[182:185], v[136:139]
	v_mfma_f32_16x16x32_bf16 v[90:93], v[132:135], v[182:185], v[90:93]
	v_mfma_f32_16x16x32_bf16 v[124:127], v[102:105], v[190:193], v[124:127]
	v_mfma_f32_16x16x32_bf16 v[86:89], v[132:135], v[190:193], v[86:89]
	v_mfma_f32_16x16x32_bf16 v[120:123], v[102:105], v[200:203], v[120:123]
	v_mfma_f32_16x16x32_bf16 v[82:85], v[132:135], v[200:203], v[82:85]
	v_mfma_f32_16x16x32_bf16 v[140:143], v[128:131], v[178:181], v[140:143]
	v_mfma_f32_16x16x32_bf16 v[94:97], v[154:157], v[178:181], v[94:97]
	v_mfma_f32_16x16x32_bf16 v[136:139], v[128:131], v[186:189], v[136:139]
	v_mfma_f32_16x16x32_bf16 v[90:93], v[154:157], v[186:189], v[90:93]
	v_mfma_f32_16x16x32_bf16 v[124:127], v[128:131], v[194:197], v[124:127]
	v_mfma_f32_16x16x32_bf16 v[86:89], v[154:157], v[194:197], v[86:89]
	v_mfma_f32_16x16x32_bf16 v[120:123], v[128:131], v[204:207], v[120:123]
	v_mfma_f32_16x16x32_bf16 v[82:85], v[154:157], v[204:207], v[82:85]
	s_setprio 0
	s_setprio 1
	v_mfma_f32_16x16x32_bf16 v[62:65], v[158:161], v[174:177], v[62:65]
	v_mfma_f32_16x16x32_bf16 v[34:37], v[166:169], v[174:177], v[34:37]
	v_mfma_f32_16x16x32_bf16 v[58:61], v[158:161], v[182:185], v[58:61]
	v_mfma_f32_16x16x32_bf16 v[26:29], v[166:169], v[182:185], v[26:29]
	v_mfma_f32_16x16x32_bf16 v[54:57], v[158:161], v[190:193], v[54:57]
	v_mfma_f32_16x16x32_bf16 v[22:25], v[166:169], v[190:193], v[22:25]
	v_mfma_f32_16x16x32_bf16 v[50:53], v[158:161], v[200:203], v[50:53]
	v_mfma_f32_16x16x32_bf16 v[18:21], v[166:169], v[200:203], v[18:21]
	v_mfma_f32_16x16x32_bf16 v[62:65], v[162:165], v[178:181], v[62:65]
	v_mfma_f32_16x16x32_bf16 v[34:37], v[170:173], v[178:181], v[34:37]
	v_mfma_f32_16x16x32_bf16 v[58:61], v[162:165], v[186:189], v[58:61]
	v_mfma_f32_16x16x32_bf16 v[26:29], v[170:173], v[186:189], v[26:29]
	v_mfma_f32_16x16x32_bf16 v[54:57], v[162:165], v[194:197], v[54:57]
	v_mfma_f32_16x16x32_bf16 v[22:25], v[170:173], v[194:197], v[22:25]
	v_mfma_f32_16x16x32_bf16 v[50:53], v[162:165], v[204:207], v[50:53]
	v_mfma_f32_16x16x32_bf16 v[18:21], v[170:173], v[204:207], v[18:21]
	s_setprio 0
	s_barrier
	s_add_u32 s98, s8, s30
	s_addc_u32 s99, s9, s31
	s_add_u32 s100, s10, s30
	s_addc_u32 s101, s11, s31
	s_add_i32 s16, s16, s5
	s_mov_b32 m0, s16
	ds_read_b128 v[174:177], v210 offset:16384
	ds_read_b128 v[178:181], v210 offset:17408
	ds_read_b128 v[182:185], v210 offset:18432
	ds_read_b128 v[186:189], v210 offset:19456
	ds_read_b128 v[190:193], v210 offset:20480
	ds_read_b128 v[194:197], v210 offset:21504
	ds_read_b128 v[200:203], v210 offset:22528
	ds_read_b128 v[204:207], v210 offset:23552
	global_load_lds_dwordx4 v0, s[8:9]
	s_add_i32 m0, s16, 0x2000
	s_add_u32 s16, s8, 0x80000
	s_addc_u32 s17, s9, 0
	s_add_i32 s22, s22, s5
	global_load_lds_dwordx4 v148, s[8:9]
	s_mov_b32 m0, s22
	s_nop 0
	global_load_lds_dwordx4 v0, s[16:17]
	s_add_i32 m0, s22, 0x2000
	s_nop 0
	global_load_lds_dwordx4 v148, s[16:17]
	s_mov_b32 m0, s20
	s_nop 0
	global_load_lds_dwordx4 v144, s[10:11]
	s_mov_b32 m0, s21
	s_nop 0
	global_load_lds_dwordx4 v146, s[10:11]
	s_waitcnt vmcnt(8)
	s_waitcnt lgkmcnt(0)
	s_barrier
	s_setprio 1
	v_mfma_f32_16x16x32_bf16 v[116:119], v[102:105], v[174:177], v[116:119]
	v_mfma_f32_16x16x32_bf16 v[78:81], v[132:135], v[174:177], v[78:81]
	v_mfma_f32_16x16x32_bf16 v[112:115], v[102:105], v[182:185], v[112:115]
	v_mfma_f32_16x16x32_bf16 v[74:77], v[132:135], v[182:185], v[74:77]
	v_mfma_f32_16x16x32_bf16 v[106:109], v[102:105], v[190:193], v[108:111]
	v_mfma_f32_16x16x32_bf16 v[70:73], v[132:135], v[190:193], v[70:73]
	v_mfma_f32_16x16x32_bf16 v[98:101], v[102:105], v[200:203], v[98:101]
	v_mfma_f32_16x16x32_bf16 v[66:69], v[132:135], v[200:203], v[66:69]
	v_mfma_f32_16x16x32_bf16 v[116:119], v[128:131], v[178:181], v[116:119]
	v_mfma_f32_16x16x32_bf16 v[78:81], v[154:157], v[178:181], v[78:81]
	v_mfma_f32_16x16x32_bf16 v[112:115], v[128:131], v[186:189], v[112:115]
	v_mfma_f32_16x16x32_bf16 v[74:77], v[154:157], v[186:189], v[74:77]
	v_mfma_f32_16x16x32_bf16 v[106:109], v[128:131], v[194:197], v[106:109]
	v_mfma_f32_16x16x32_bf16 v[70:73], v[154:157], v[194:197], v[70:73]
	v_mfma_f32_16x16x32_bf16 v[98:101], v[128:131], v[204:207], v[98:101]
	v_mfma_f32_16x16x32_bf16 v[66:69], v[154:157], v[204:207], v[66:69]
	s_setprio 0
	s_setprio 1
	v_mfma_f32_16x16x32_bf16 v[46:49], v[158:161], v[174:177], v[46:49]
	v_mfma_f32_16x16x32_bf16 v[14:17], v[166:169], v[174:177], v[14:17]
	v_mfma_f32_16x16x32_bf16 v[42:45], v[158:161], v[182:185], v[42:45]
	v_mfma_f32_16x16x32_bf16 v[10:13], v[166:169], v[182:185], v[10:13]
	v_mfma_f32_16x16x32_bf16 v[38:41], v[158:161], v[190:193], v[38:41]
	v_mfma_f32_16x16x32_bf16 v[6:9], v[166:169], v[190:193], v[6:9]
	v_mfma_f32_16x16x32_bf16 v[30:33], v[158:161], v[200:203], v[30:33]
	v_mfma_f32_16x16x32_bf16 v[2:5], v[166:169], v[200:203], v[2:5]
	v_mfma_f32_16x16x32_bf16 v[46:49], v[162:165], v[178:181], v[46:49]
	v_mfma_f32_16x16x32_bf16 v[14:17], v[170:173], v[178:181], v[14:17]
	v_mfma_f32_16x16x32_bf16 v[42:45], v[162:165], v[186:189], v[42:45]
	v_mfma_f32_16x16x32_bf16 v[10:13], v[170:173], v[186:189], v[10:13]
	v_mfma_f32_16x16x32_bf16 v[38:41], v[162:165], v[194:197], v[38:41]
	v_mfma_f32_16x16x32_bf16 v[6:9], v[170:173], v[194:197], v[6:9]
	v_mfma_f32_16x16x32_bf16 v[30:33], v[162:165], v[204:207], v[30:33]
	v_mfma_f32_16x16x32_bf16 v[2:5], v[170:173], v[204:207], v[2:5]
	s_setprio 0
	s_barrier
; #define PG8_STAGE(bufoff, gbase, voff) do { _Pragma("unroll") for (int _i = 0; _i < 2; ++_i) \
;         __builtin_amdgcn_global_load_lds((const unsigned*)((const char*)(gbase) + (voff)[_i]), (LAS unsigned*)(lds + (bufoff) + ldsw + _i * 8192), 16, 0, 0); } while (0)
; #define PG8_LDA(dst, b, h) do { _Pragma("unroll") for (int m = 0; m < 4; ++m) _Pragma("unroll") for (int k = 0; k < 2; ++k) dst[m][k] = *(const LAS bf16x8*)(lds + PG8_SA(b, h) + aoff + m * 2048 + k * 1024); } while (0)
; #define PG8_LDB(dst, b, h) do { _Pragma("unroll") for (int n = 0; n < 2; ++n) _Pragma("unroll") for (int k = 0; k < 2; ++k) dst[n][k] = *(const LAS bf16x8*)(lds + PG8_SB(b, h) + boff + n * 2048 + k * 1024); } while (0)
; #define PG8_MMA(ai, bj, At, Bt) do { __builtin_amdgcn_s_setprio(1); _Pragma("unroll") for (int m = 0; m < 4; ++m) _Pragma("unroll") for (int n = 0; n < 2; ++n) _Pragma("unroll") for (int k = 0; k < 2; ++k) \
;         acc[ai][bj][m][n] = __builtin_amdgcn_mfma_f32_16x16x32_bf16(Bt[n][k], At[m][k], acc[ai][bj][m][n], 0, 0, 0); __builtin_amdgcn_s_setprio(0); } while (0)
; #define PG8_WAIT_V(n) asm volatile("s_waitcnt vmcnt(" #n ")" ::: "memory")
; #define PG8_WAIT_L(n) asm volatile("s_waitcnt lgkmcnt(" #n ")" ::: "memory")
; #define PG8_BAR __builtin_amdgcn_s_barrier()
; #define PG8_SCHED __builtin_amdgcn_sched_barrier(0)
; template <class Epi, class Sched>
; __device__ __forceinline__ void gemm_phase(LAS unsigned char* lds, const int lda, const int ldb, const int K, const Sched& S, const Epi& E, int tid) {
;     ...
;             PG8_LDB(B0, 1, 0); PG8_LDB(B1, 1, 1); PG8_SCHED; PG8_LDA(At, 1, 0); PG8_STAGE(PG8_SA(0, 1), a2 + hA, voffA);
;             PG8_WAIT_V(8); PG8_WAIT_L(0); PG8_BAR; PG8_MMA(0, 0, At, B0); PG8_MMA(0, 1, At, B1); PG8_BAR; PG8_SCHED;
;             PG8_LDA(At, 1, 1); PG8_STAGE(PG8_SB(1, 0), b3, voffB); PG8_STAGE(PG8_SB(1, 1), b3 + hB, voffB); PG8_STAGE(PG8_SA(1, 0), a3, voffA);
;             PG8_WAIT_V(8); PG8_WAIT_L(0); PG8_BAR; PG8_MMA(1, 0, At, B0); PG8_MMA(1, 1, At, B1); PG8_BAR; PG8_SCHED;
;         }
;         if (wr == 0) PG8_BAR;
	s_add_i32 s16, 0, 0x18000
	v_add_u32_e32 v110, s16, v208
	s_add_i32 s17, 0, 0x1c000
	ds_read_b128 v[102:105], v110
	ds_read_b128 v[128:131], v110 offset:1024
	ds_read_b128 v[132:135], v110 offset:2048
	ds_read_b128 v[154:157], v110 offset:3072
	v_add_u32_e32 v110, s17, v208
	ds_read_b128 v[158:161], v110
	ds_read_b128 v[162:165], v110 offset:1024
	ds_read_b128 v[166:169], v110 offset:2048
	ds_read_b128 v[170:173], v110 offset:3072
	s_add_u32 s10, s10, 0x80000
	s_addc_u32 s11, s11, 0
	s_mov_b32 m0, s26
	ds_read_b128 v[174:177], v210 offset:32768
	ds_read_b128 v[178:181], v210 offset:33792
	ds_read_b128 v[182:185], v210 offset:34816
	ds_read_b128 v[186:189], v210 offset:35840
	ds_read_b128 v[190:193], v210 offset:36864
	ds_read_b128 v[194:197], v210 offset:37888
	ds_read_b128 v[200:203], v210 offset:38912
	ds_read_b128 v[204:207], v210 offset:39936
	global_load_lds_dwordx4 v144, s[10:11]
	s_mov_b32 m0, s27
	s_nop 0
	global_load_lds_dwordx4 v146, s[10:11]
	s_waitcnt vmcnt(8)
	s_waitcnt lgkmcnt(0)
	s_barrier
	s_setprio 1
	v_mfma_f32_16x16x32_bf16 v[140:143], v[102:105], v[174:177], v[140:143]
	v_mfma_f32_16x16x32_bf16 v[94:97], v[132:135], v[174:177], v[94:97]
	v_mfma_f32_16x16x32_bf16 v[136:139], v[102:105], v[182:185], v[136:139]
	v_mfma_f32_16x16x32_bf16 v[90:93], v[132:135], v[182:185], v[90:93]
	v_mfma_f32_16x16x32_bf16 v[124:127], v[102:105], v[190:193], v[124:127]
	v_mfma_f32_16x16x32_bf16 v[86:89], v[132:135], v[190:193], v[86:89]
	v_mfma_f32_16x16x32_bf16 v[120:123], v[102:105], v[200:203], v[120:123]
	v_mfma_f32_16x16x32_bf16 v[82:85], v[132:135], v[200:203], v[82:85]
	v_mfma_f32_16x16x32_bf16 v[140:143], v[128:131], v[178:181], v[140:143]
	v_mfma_f32_16x16x32_bf16 v[94:97], v[154:157], v[178:181], v[94:97]
	v_mfma_f32_16x16x32_bf16 v[136:139], v[128:131], v[186:189], v[136:139]
	v_mfma_f32_16x16x32_bf16 v[90:93], v[154:157], v[186:189], v[90:93]
	v_mfma_f32_16x16x32_bf16 v[124:127], v[128:131], v[194:197], v[124:127]
	v_mfma_f32_16x16x32_bf16 v[86:89], v[154:157], v[194:197], v[86:89]
	v_mfma_f32_16x16x32_bf16 v[120:123], v[128:131], v[204:207], v[120:123]
	v_mfma_f32_16x16x32_bf16 v[82:85], v[154:157], v[204:207], v[82:85]
	s_setprio 0
	s_setprio 1
	v_mfma_f32_16x16x32_bf16 v[62:65], v[158:161], v[174:177], v[62:65]
	v_mfma_f32_16x16x32_bf16 v[34:37], v[166:169], v[174:177], v[34:37]
	v_mfma_f32_16x16x32_bf16 v[58:61], v[158:161], v[182:185], v[58:61]
	v_mfma_f32_16x16x32_bf16 v[26:29], v[166:169], v[182:185], v[26:29]
	v_mfma_f32_16x16x32_bf16 v[54:57], v[158:161], v[190:193], v[54:57]
	v_mfma_f32_16x16x32_bf16 v[22:25], v[166:169], v[190:193], v[22:25]
	v_mfma_f32_16x16x32_bf16 v[50:53], v[158:161], v[200:203], v[50:53]
	v_mfma_f32_16x16x32_bf16 v[18:21], v[166:169], v[200:203], v[18:21]
	v_mfma_f32_16x16x32_bf16 v[62:65], v[162:165], v[178:181], v[62:65]
	v_mfma_f32_16x16x32_bf16 v[34:37], v[170:173], v[178:181], v[34:37]
	v_mfma_f32_16x16x32_bf16 v[58:61], v[162:165], v[186:189], v[58:61]
	v_mfma_f32_16x16x32_bf16 v[26:29], v[170:173], v[186:189], v[26:29]
	v_mfma_f32_16x16x32_bf16 v[54:57], v[162:165], v[194:197], v[54:57]
	v_mfma_f32_16x16x32_bf16 v[22:25], v[170:173], v[194:197], v[22:25]
	v_mfma_f32_16x16x32_bf16 v[50:53], v[162:165], v[204:207], v[50:53]
	v_mfma_f32_16x16x32_bf16 v[18:21], v[170:173], v[204:207], v[18:21]
	s_setprio 0
	s_barrier
	s_add_i32 s10, s16, s5
	s_mov_b32 m0, s10
	ds_read_b128 v[174:177], v210 offset:49152
	ds_read_b128 v[178:181], v210 offset:50176
	ds_read_b128 v[182:185], v210 offset:51200
	ds_read_b128 v[186:189], v210 offset:52224
	ds_read_b128 v[190:193], v210 offset:53248
	ds_read_b128 v[194:197], v210 offset:54272
	ds_read_b128 v[200:203], v210 offset:55296
	ds_read_b128 v[204:207], v210 offset:56320
	global_load_lds_dwordx4 v0, s[98:99]
	s_add_i32 m0, s10, 0x2000
	s_add_u32 s8, s8, 0x80080
	s_addc_u32 s9, s9, 0
	s_add_i32 s10, s17, s5
	global_load_lds_dwordx4 v148, s[98:99]
	s_mov_b32 m0, s10
	s_nop 0
	global_load_lds_dwordx4 v0, s[8:9]
	s_add_i32 m0, s10, 0x2000
	s_nop 0
	global_load_lds_dwordx4 v148, s[8:9]
	s_mov_b32 m0, s25
	s_nop 0
	global_load_lds_dwordx4 v144, s[100:101]
	s_mov_b32 m0, s56
	s_nop 0
	global_load_lds_dwordx4 v146, s[100:101]
	s_waitcnt vmcnt(8)
	s_waitcnt lgkmcnt(0)
	s_barrier
	s_setprio 1
	v_mfma_f32_16x16x32_bf16 v[116:119], v[102:105], v[174:177], v[116:119]
	v_mfma_f32_16x16x32_bf16 v[78:81], v[132:135], v[174:177], v[78:81]
	v_mfma_f32_16x16x32_bf16 v[110:113], v[102:105], v[182:185], v[112:115]
	v_mfma_f32_16x16x32_bf16 v[74:77], v[132:135], v[182:185], v[74:77]
	v_mfma_f32_16x16x32_bf16 v[106:109], v[102:105], v[190:193], v[106:109]
	v_mfma_f32_16x16x32_bf16 v[70:73], v[132:135], v[190:193], v[70:73]
	v_mfma_f32_16x16x32_bf16 v[98:101], v[102:105], v[200:203], v[98:101]
	v_mfma_f32_16x16x32_bf16 v[66:69], v[132:135], v[200:203], v[66:69]
	v_mfma_f32_16x16x32_bf16 v[116:119], v[128:131], v[178:181], v[116:119]
	v_mfma_f32_16x16x32_bf16 v[78:81], v[154:157], v[178:181], v[78:81]
	v_mfma_f32_16x16x32_bf16 v[112:115], v[128:131], v[186:189], v[110:113]
	v_mfma_f32_16x16x32_bf16 v[74:77], v[154:157], v[186:189], v[74:77]
	v_mfma_f32_16x16x32_bf16 v[108:111], v[128:131], v[194:197], v[106:109]
	v_mfma_f32_16x16x32_bf16 v[70:73], v[154:157], v[194:197], v[70:73]
	v_mfma_f32_16x16x32_bf16 v[98:101], v[128:131], v[204:207], v[98:101]
	v_mfma_f32_16x16x32_bf16 v[66:69], v[154:157], v[204:207], v[66:69]
	s_setprio 0
	s_setprio 1
	v_mfma_f32_16x16x32_bf16 v[46:49], v[158:161], v[174:177], v[46:49]
	v_mfma_f32_16x16x32_bf16 v[14:17], v[166:169], v[174:177], v[14:17]
	v_mfma_f32_16x16x32_bf16 v[42:45], v[158:161], v[182:185], v[42:45]
	v_mfma_f32_16x16x32_bf16 v[10:13], v[166:169], v[182:185], v[10:13]
	v_mfma_f32_16x16x32_bf16 v[38:41], v[158:161], v[190:193], v[38:41]
	v_mfma_f32_16x16x32_bf16 v[6:9], v[166:169], v[190:193], v[6:9]
	v_mfma_f32_16x16x32_bf16 v[30:33], v[158:161], v[200:203], v[30:33]
	v_mfma_f32_16x16x32_bf16 v[2:5], v[166:169], v[200:203], v[2:5]
	v_mfma_f32_16x16x32_bf16 v[46:49], v[162:165], v[178:181], v[46:49]
	v_mfma_f32_16x16x32_bf16 v[14:17], v[170:173], v[178:181], v[14:17]
	v_mfma_f32_16x16x32_bf16 v[42:45], v[162:165], v[186:189], v[42:45]
	v_mfma_f32_16x16x32_bf16 v[10:13], v[170:173], v[186:189], v[10:13]
	v_mfma_f32_16x16x32_bf16 v[38:41], v[162:165], v[194:197], v[38:41]
	v_mfma_f32_16x16x32_bf16 v[6:9], v[170:173], v[194:197], v[6:9]
	v_mfma_f32_16x16x32_bf16 v[30:33], v[162:165], v[204:207], v[30:33]
	v_mfma_f32_16x16x32_bf16 v[2:5], v[170:173], v[204:207], v[2:5]
	s_setprio 0
	s_barrier
	s_add_i32 s15, s15, 2
	s_add_u32 s6, s6, 0x100
	s_addc_u32 s7, s7, 0
	s_add_u32 s3, s3, 0x100
	s_addc_u32 s14, s14, 0
	s_cmp_gt_u32 s15, 29
	s_cbranch_scc0 .LBB0_530
	s_and_b64 vcc, exec, s[48:49]
	s_cbranch_vccz .LBB0_533
	s_barrier

; #define PG8_STAGE(bufoff, gbase, voff) do { _Pragma("unroll") for (int _i = 0; _i < 2; ++_i) \
;         __builtin_amdgcn_global_load_lds((const unsigned*)((const char*)(gbase) + (voff)[_i]), (LAS unsigned*)(lds + (bufoff) + ldsw + _i * 8192), 16, 0, 0); } while (0)
; #define PG8_LDA(dst, b, h) do { _Pragma("unroll") for (int m = 0; m < 4; ++m) _Pragma("unroll") for (int k = 0; k < 2; ++k) dst[m][k] = *(const LAS bf16x8*)(lds + PG8_SA(b, h) + aoff + m * 2048 + k * 1024); } while (0)
; #define PG8_LDB(dst, b, h) do { _Pragma("unroll") for (int n = 0; n < 2; ++n) _Pragma("unroll") for (int k = 0; k < 2; ++k) dst[n][k] = *(const LAS bf16x8*)(lds + PG8_SB(b, h) + boff + n * 2048 + k * 1024); } while (0)
; #define PG8_MMA(ai, bj, At, Bt) do { __builtin_amdgcn_s_setprio(1); _Pragma("unroll") for (int m = 0; m < 4; ++m) _Pragma("unroll") for (int n = 0; n < 2; ++n) _Pragma("unroll") for (int k = 0; k < 2; ++k) \
;         acc[ai][bj][m][n] = __builtin_amdgcn_mfma_f32_16x16x32_bf16(Bt[n][k], At[m][k], acc[ai][bj][m][n], 0, 0, 0); __builtin_amdgcn_s_setprio(0); } while (0)
; #define PG8_WAIT_V(n) asm volatile("s_waitcnt vmcnt(" #n ")" ::: "memory")
; #define PG8_WAIT_L(n) asm volatile("s_waitcnt lgkmcnt(" #n ")" ::: "memory")
; #define PG8_BAR __builtin_amdgcn_s_barrier()
; #define PG8_SCHED __builtin_amdgcn_sched_barrier(0)
; template <class Epi, class Sched>
; __device__ __forceinline__ void gemm_phase(LAS unsigned char* lds, const int lda, const int ldb, const int K, const Sched& S, const Epi& E, int tid) {
;     ...
;             const bool last = (t == nt - 2);
;             const char* a1 = cA + (size_t)(t + 1) * kstep;
;             const char* a2 = last ? nA : cA + (size_t)(t + 2) * kstep; const char* b2 = last ? nB : cB + (size_t)(t + 2) * kstep;
;             const char* a3 = a2 + kstep; const char* b3 = b2 + kstep;
;             PG8_LDB(B0, 0, 0); PG8_LDB(B1, 0, 1); PG8_SCHED; PG8_LDA(At, 0, 0); PG8_STAGE(PG8_SA(1, 1), a1 + hA, voffA);
;             PG8_WAIT_V(8); PG8_WAIT_L(0); PG8_BAR; PG8_MMA(0, 0, At, B0); PG8_MMA(0, 1, At, B1); PG8_BAR; PG8_SCHED;
;             PG8_LDA(At, 0, 1); PG8_STAGE(PG8_SB(0, 0), b2, voffB); PG8_STAGE(PG8_SB(0, 1), b2 + hB, voffB); PG8_STAGE(PG8_SA(0, 0), a2, voffA);
;             PG8_WAIT_V(8); PG8_WAIT_L(0); PG8_BAR; PG8_MMA(1, 0, At, B0); PG8_MMA(1, 1, At, B1); PG8_BAR; PG8_SCHED;
.LBB0_681:
	s_add_u32 s26, s56, 0xfff80080
	s_addc_u32 s27, s57, -1
	s_add_i32 s34, 0, 0x10000
	s_cmp_eq_u32 s60, 28
	s_cselect_b32 vcc_hi, s9, s27
	s_cselect_b32 vcc_lo, s8, s26
	v_add_u32_e32 v0, s34, v198
	s_cselect_b32 s27, s11, s19
	s_cselect_b32 s26, s10, s17
	s_add_i32 s76, 0, 0x14000
	ds_read_b128 v[114:117], v0
	ds_read_b128 v[118:121], v0 offset:1024
	ds_read_b128 v[122:125], v0 offset:2048
	ds_read_b128 v[126:129], v0 offset:3072
	v_add_u32_e32 v0, s76, v198
	ds_read_b128 v[130:133], v0
	ds_read_b128 v[134:137], v0 offset:1024
	ds_read_b128 v[138:141], v0 offset:2048
	ds_read_b128 v[142:145], v0 offset:3072
	s_add_i32 m0, s29, 0xc000
	ds_read_b128 v[162:165], v237
	ds_read_b128 v[166:169], v237 offset:1024
	ds_read_b128 v[202:205], v237 offset:2048
	ds_read_b128 v[206:209], v237 offset:3072
	ds_read_b128 v[210:213], v237 offset:4096
	ds_read_b128 v[214:217], v237 offset:5120
	ds_read_b128 v[218:221], v237 offset:6144
	ds_read_b128 v[240:243], v237 offset:7168
	global_load_lds_dwordx4 v196, s[56:57]
	s_add_i32 m0, s29, 0xe000
	s_nop 0
	global_load_lds_dwordx4 v200, s[56:57]
	s_waitcnt vmcnt(8)
	s_waitcnt lgkmcnt(0)
	s_barrier
	s_setprio 1
	v_mfma_f32_16x16x32_bf16 v[158:161], v[114:117], v[162:165], v[158:161]
	v_mfma_f32_16x16x32_bf16 v[62:65], v[122:125], v[162:165], v[62:65]
	v_mfma_f32_16x16x32_bf16 v[150:153], v[114:117], v[202:205], v[150:153]
	v_mfma_f32_16x16x32_bf16 v[54:57], v[122:125], v[202:205], v[54:57]
	v_mfma_f32_16x16x32_bf16 v[110:113], v[114:117], v[210:213], v[110:113]
	v_mfma_f32_16x16x32_bf16 v[46:49], v[122:125], v[210:213], v[46:49]
	v_mfma_f32_16x16x32_bf16 v[102:105], v[114:117], v[218:221], v[102:105]
	v_mfma_f32_16x16x32_bf16 v[38:41], v[122:125], v[218:221], v[38:41]
	v_mfma_f32_16x16x32_bf16 v[158:161], v[118:121], v[166:169], v[158:161]
	v_mfma_f32_16x16x32_bf16 v[62:65], v[126:129], v[166:169], v[62:65]
	v_mfma_f32_16x16x32_bf16 v[150:153], v[118:121], v[206:209], v[150:153]
	v_mfma_f32_16x16x32_bf16 v[54:57], v[126:129], v[206:209], v[54:57]
	v_mfma_f32_16x16x32_bf16 v[110:113], v[118:121], v[214:217], v[110:113]
	v_mfma_f32_16x16x32_bf16 v[46:49], v[126:129], v[214:217], v[46:49]
	v_mfma_f32_16x16x32_bf16 v[102:105], v[118:121], v[240:243], v[102:105]
	v_mfma_f32_16x16x32_bf16 v[38:41], v[126:129], v[240:243], v[38:41]
	s_setprio 0
	s_setprio 1
	v_mfma_f32_16x16x32_bf16 v[154:157], v[130:133], v[162:165], v[154:157]
	v_mfma_f32_16x16x32_bf16 v[58:61], v[138:141], v[162:165], v[58:61]
	v_mfma_f32_16x16x32_bf16 v[146:149], v[130:133], v[202:205], v[146:149]
	v_mfma_f32_16x16x32_bf16 v[50:53], v[138:141], v[202:205], v[50:53]
	v_mfma_f32_16x16x32_bf16 v[106:109], v[130:133], v[210:213], v[106:109]
	v_mfma_f32_16x16x32_bf16 v[42:45], v[138:141], v[210:213], v[42:45]
	v_mfma_f32_16x16x32_bf16 v[98:101], v[130:133], v[218:221], v[98:101]
	v_mfma_f32_16x16x32_bf16 v[34:37], v[138:141], v[218:221], v[34:37]
	v_mfma_f32_16x16x32_bf16 v[154:157], v[134:137], v[166:169], v[154:157]
	v_mfma_f32_16x16x32_bf16 v[58:61], v[142:145], v[166:169], v[58:61]
	v_mfma_f32_16x16x32_bf16 v[146:149], v[134:137], v[206:209], v[146:149]
	v_mfma_f32_16x16x32_bf16 v[50:53], v[142:145], v[206:209], v[50:53]
	v_mfma_f32_16x16x32_bf16 v[106:109], v[134:137], v[214:217], v[106:109]
	v_mfma_f32_16x16x32_bf16 v[42:45], v[142:145], v[214:217], v[42:45]
	v_mfma_f32_16x16x32_bf16 v[98:101], v[134:137], v[240:243], v[98:101]
	v_mfma_f32_16x16x32_bf16 v[34:37], v[142:145], v[240:243], v[34:37]
	s_setprio 0
	s_barrier
	s_add_i32 s34, s34, s28
	s_mov_b32 m0, s34
	ds_read_b128 v[162:165], v237 offset:16384
	ds_read_b128 v[166:169], v237 offset:17408
	ds_read_b128 v[202:205], v237 offset:18432
	ds_read_b128 v[206:209], v237 offset:19456
	ds_read_b128 v[210:213], v237 offset:20480
	ds_read_b128 v[214:217], v237 offset:21504
	ds_read_b128 v[218:221], v237 offset:22528
	ds_read_b128 v[240:243], v237 offset:23552
	global_load_lds_dwordx4 v172, s[26:27]
	s_add_i32 m0, s34, 0x2000
	s_add_u32 s34, s26, 0x80000
	s_addc_u32 s35, s27, 0
	s_add_i32 s76, s76, s28
	global_load_lds_dwordx4 v176, s[26:27]
	s_mov_b32 m0, s76
	s_nop 0
	global_load_lds_dwordx4 v172, s[34:35]
	s_add_i32 m0, s76, 0x2000
	s_nop 0
	global_load_lds_dwordx4 v176, s[34:35]
	s_mov_b32 m0, s29
	s_nop 0
	global_load_lds_dwordx4 v170, vcc
	s_mov_b32 m0, s67
	s_nop 0
	global_load_lds_dwordx4 v174, vcc
	s_waitcnt vmcnt(8)
	s_waitcnt lgkmcnt(0)
	s_barrier
	s_setprio 1
	v_mfma_f32_16x16x32_bf16 v[94:97], v[114:117], v[162:165], v[94:97]
	v_mfma_f32_16x16x32_bf16 v[30:33], v[122:125], v[162:165], v[30:33]
	v_mfma_f32_16x16x32_bf16 v[86:89], v[114:117], v[202:205], v[86:89]
	v_mfma_f32_16x16x32_bf16 v[22:25], v[122:125], v[202:205], v[22:25]
	v_mfma_f32_16x16x32_bf16 v[78:81], v[114:117], v[210:213], v[78:81]
	v_mfma_f32_16x16x32_bf16 v[14:17], v[122:125], v[210:213], v[14:17]
	v_mfma_f32_16x16x32_bf16 v[70:73], v[114:117], v[218:221], v[70:73]
	v_mfma_f32_16x16x32_bf16 v[6:9], v[122:125], v[218:221], v[6:9]
	v_mfma_f32_16x16x32_bf16 v[94:97], v[118:121], v[166:169], v[94:97]
	v_mfma_f32_16x16x32_bf16 v[30:33], v[126:129], v[166:169], v[30:33]
	v_mfma_f32_16x16x32_bf16 v[86:89], v[118:121], v[206:209], v[86:89]
	v_mfma_f32_16x16x32_bf16 v[22:25], v[126:129], v[206:209], v[22:25]
	v_mfma_f32_16x16x32_bf16 v[78:81], v[118:121], v[214:217], v[78:81]
	v_mfma_f32_16x16x32_bf16 v[14:17], v[126:129], v[214:217], v[14:17]
	v_mfma_f32_16x16x32_bf16 v[70:73], v[118:121], v[240:243], v[70:73]
	v_mfma_f32_16x16x32_bf16 v[6:9], v[126:129], v[240:243], v[6:9]
	s_setprio 0
	s_setprio 1
	v_mfma_f32_16x16x32_bf16 v[90:93], v[130:133], v[162:165], v[90:93]
	v_mfma_f32_16x16x32_bf16 v[26:29], v[138:141], v[162:165], v[26:29]
	v_mfma_f32_16x16x32_bf16 v[82:85], v[130:133], v[202:205], v[82:85]
	v_mfma_f32_16x16x32_bf16 v[18:21], v[138:141], v[202:205], v[18:21]
	v_mfma_f32_16x16x32_bf16 v[74:77], v[130:133], v[210:213], v[74:77]
	v_mfma_f32_16x16x32_bf16 v[10:13], v[138:141], v[210:213], v[10:13]
	v_mfma_f32_16x16x32_bf16 v[66:69], v[130:133], v[218:221], v[66:69]
	v_mfma_f32_16x16x32_bf16 v[2:5], v[138:141], v[218:221], v[2:5]
	v_mfma_f32_16x16x32_bf16 v[90:93], v[134:137], v[166:169], v[90:93]
	v_mfma_f32_16x16x32_bf16 v[26:29], v[142:145], v[166:169], v[26:29]
	v_mfma_f32_16x16x32_bf16 v[82:85], v[134:137], v[206:209], v[82:85]
	v_mfma_f32_16x16x32_bf16 v[18:21], v[142:145], v[206:209], v[18:21]
	v_mfma_f32_16x16x32_bf16 v[74:77], v[134:137], v[214:217], v[74:77]
	v_mfma_f32_16x16x32_bf16 v[10:13], v[142:145], v[214:217], v[10:13]
	v_mfma_f32_16x16x32_bf16 v[66:69], v[134:137], v[240:243], v[66:69]
	v_mfma_f32_16x16x32_bf16 v[2:5], v[142:145], v[240:243], v[2:5]
	s_setprio 0
	s_barrier
; #define PG8_STAGE(bufoff, gbase, voff) do { _Pragma("unroll") for (int _i = 0; _i < 2; ++_i) \
;         __builtin_amdgcn_global_load_lds((const unsigned*)((const char*)(gbase) + (voff)[_i]), (LAS unsigned*)(lds + (bufoff) + ldsw + _i * 8192), 16, 0, 0); } while (0)
; #define PG8_LDA(dst, b, h) do { _Pragma("unroll") for (int m = 0; m < 4; ++m) _Pragma("unroll") for (int k = 0; k < 2; ++k) dst[m][k] = *(const LAS bf16x8*)(lds + PG8_SA(b, h) + aoff + m * 2048 + k * 1024); } while (0)
; #define PG8_LDB(dst, b, h) do { _Pragma("unroll") for (int n = 0; n < 2; ++n) _Pragma("unroll") for (int k = 0; k < 2; ++k) dst[n][k] = *(const LAS bf16x8*)(lds + PG8_SB(b, h) + boff + n * 2048 + k * 1024); } while (0)
; #define PG8_MMA(ai, bj, At, Bt) do { __builtin_amdgcn_s_setprio(1); _Pragma("unroll") for (int m = 0; m < 4; ++m) _Pragma("unroll") for (int n = 0; n < 2; ++n) _Pragma("unroll") for (int k = 0; k < 2; ++k) \
;         acc[ai][bj][m][n] = __builtin_amdgcn_mfma_f32_16x16x32_bf16(Bt[n][k], At[m][k], acc[ai][bj][m][n], 0, 0, 0); __builtin_amdgcn_s_setprio(0); } while (0)
; #define PG8_WAIT_V(n) asm volatile("s_waitcnt vmcnt(" #n ")" ::: "memory")
; #define PG8_WAIT_L(n) asm volatile("s_waitcnt lgkmcnt(" #n ")" ::: "memory")
; #define PG8_BAR __builtin_amdgcn_s_barrier()
; #define PG8_SCHED __builtin_amdgcn_sched_barrier(0)
; template <class Epi, class Sched>
; __device__ __forceinline__ void gemm_phase(LAS unsigned char* lds, const int lda, const int ldb, const int K, const Sched& S, const Epi& E, int tid) {
;     ...
;             PG8_LDB(B0, 1, 0); PG8_LDB(B1, 1, 1); PG8_SCHED; PG8_LDA(At, 1, 0); PG8_STAGE(PG8_SA(0, 1), a2 + hA, voffA);
;             PG8_WAIT_V(8); PG8_WAIT_L(0); PG8_BAR; PG8_MMA(0, 0, At, B0); PG8_MMA(0, 1, At, B1); PG8_BAR; PG8_SCHED;
;             PG8_LDA(At, 1, 1); PG8_STAGE(PG8_SB(1, 0), b3, voffB); PG8_STAGE(PG8_SB(1, 1), b3 + hB, voffB); PG8_STAGE(PG8_SA(1, 0), a3, voffA);
;             PG8_WAIT_V(8); PG8_WAIT_L(0); PG8_BAR; PG8_MMA(1, 0, At, B0); PG8_MMA(1, 1, At, B1); PG8_BAR; PG8_SCHED;
;         }
;         if (wr == 0) PG8_BAR;
	s_add_i32 s76, 0, 0x18000
	v_add_u32_e32 v0, s76, v198
	s_add_i32 s94, 0, 0x1c000
	ds_read_b128 v[114:117], v0
	ds_read_b128 v[118:121], v0 offset:1024
	ds_read_b128 v[122:125], v0 offset:2048
	ds_read_b128 v[126:129], v0 offset:3072
	v_add_u32_e32 v0, s94, v198
	ds_read_b128 v[130:133], v0
	ds_read_b128 v[134:137], v0 offset:1024
	ds_read_b128 v[138:141], v0 offset:2048
	ds_read_b128 v[142:145], v0 offset:3072
	s_add_u32 s34, vcc_lo, 0x80000
	s_addc_u32 s35, vcc_hi, 0
	s_mov_b32 m0, s25
	ds_read_b128 v[162:165], v237 offset:32768
	ds_read_b128 v[166:169], v237 offset:33792
	ds_read_b128 v[202:205], v237 offset:34816
	ds_read_b128 v[206:209], v237 offset:35840
	ds_read_b128 v[210:213], v237 offset:36864
	ds_read_b128 v[214:217], v237 offset:37888
	ds_read_b128 v[218:221], v237 offset:38912
	ds_read_b128 v[240:243], v237 offset:39936
	global_load_lds_dwordx4 v170, s[34:35]
	s_mov_b32 m0, s0
	s_nop 0
	global_load_lds_dwordx4 v174, s[34:35]
	s_waitcnt vmcnt(8)
	s_waitcnt lgkmcnt(0)
	s_barrier
	s_setprio 1
	v_mfma_f32_16x16x32_bf16 v[158:161], v[114:117], v[162:165], v[158:161]
	v_mfma_f32_16x16x32_bf16 v[62:65], v[122:125], v[162:165], v[62:65]
	v_mfma_f32_16x16x32_bf16 v[150:153], v[114:117], v[202:205], v[150:153]
	v_mfma_f32_16x16x32_bf16 v[54:57], v[122:125], v[202:205], v[54:57]
	v_mfma_f32_16x16x32_bf16 v[110:113], v[114:117], v[210:213], v[110:113]
	v_mfma_f32_16x16x32_bf16 v[46:49], v[122:125], v[210:213], v[46:49]
	v_mfma_f32_16x16x32_bf16 v[102:105], v[114:117], v[218:221], v[102:105]
	v_mfma_f32_16x16x32_bf16 v[38:41], v[122:125], v[218:221], v[38:41]
	v_mfma_f32_16x16x32_bf16 v[158:161], v[118:121], v[166:169], v[158:161]
	v_mfma_f32_16x16x32_bf16 v[62:65], v[126:129], v[166:169], v[62:65]
	v_mfma_f32_16x16x32_bf16 v[150:153], v[118:121], v[206:209], v[150:153]
	v_mfma_f32_16x16x32_bf16 v[54:57], v[126:129], v[206:209], v[54:57]
	v_mfma_f32_16x16x32_bf16 v[110:113], v[118:121], v[214:217], v[110:113]
	v_mfma_f32_16x16x32_bf16 v[46:49], v[126:129], v[214:217], v[46:49]
	v_mfma_f32_16x16x32_bf16 v[102:105], v[118:121], v[240:243], v[102:105]
	v_mfma_f32_16x16x32_bf16 v[38:41], v[126:129], v[240:243], v[38:41]
	s_setprio 0
	s_setprio 1
	v_mfma_f32_16x16x32_bf16 v[154:157], v[130:133], v[162:165], v[154:157]
	v_mfma_f32_16x16x32_bf16 v[58:61], v[138:141], v[162:165], v[58:61]
	v_mfma_f32_16x16x32_bf16 v[146:149], v[130:133], v[202:205], v[146:149]
	v_mfma_f32_16x16x32_bf16 v[50:53], v[138:141], v[202:205], v[50:53]
	v_mfma_f32_16x16x32_bf16 v[106:109], v[130:133], v[210:213], v[106:109]
	v_mfma_f32_16x16x32_bf16 v[42:45], v[138:141], v[210:213], v[42:45]
	v_mfma_f32_16x16x32_bf16 v[98:101], v[130:133], v[218:221], v[98:101]
	v_mfma_f32_16x16x32_bf16 v[34:37], v[138:141], v[218:221], v[34:37]
	v_mfma_f32_16x16x32_bf16 v[154:157], v[134:137], v[166:169], v[154:157]
	v_mfma_f32_16x16x32_bf16 v[58:61], v[142:145], v[166:169], v[58:61]
	v_mfma_f32_16x16x32_bf16 v[146:149], v[134:137], v[206:209], v[146:149]
	v_mfma_f32_16x16x32_bf16 v[50:53], v[142:145], v[206:209], v[50:53]
	v_mfma_f32_16x16x32_bf16 v[106:109], v[134:137], v[214:217], v[106:109]
	v_mfma_f32_16x16x32_bf16 v[42:45], v[142:145], v[214:217], v[42:45]
	v_mfma_f32_16x16x32_bf16 v[98:101], v[134:137], v[240:243], v[98:101]
	v_mfma_f32_16x16x32_bf16 v[34:37], v[142:145], v[240:243], v[34:37]
	s_setprio 0
	s_barrier
	s_add_i32 s34, s76, s28
	s_add_u32 s98, s26, s30
	s_addc_u32 s99, s27, s31
	s_mov_b32 m0, s34
	ds_read_b128 v[162:165], v237 offset:49152
	ds_read_b128 v[166:169], v237 offset:50176
	ds_read_b128 v[202:205], v237 offset:51200
	ds_read_b128 v[206:209], v237 offset:52224
	ds_read_b128 v[210:213], v237 offset:53248
	ds_read_b128 v[214:217], v237 offset:54272
	ds_read_b128 v[218:221], v237 offset:55296
	ds_read_b128 v[240:243], v237 offset:56320
	global_load_lds_dwordx4 v172, s[98:99]
	s_add_i32 m0, s34, 0x2000
	s_add_u32 s26, s26, 0x80080
	s_addc_u32 s27, s27, 0
	s_add_i32 s34, s94, s28
	global_load_lds_dwordx4 v176, s[98:99]
	s_mov_b32 m0, s34
	s_nop 0
	global_load_lds_dwordx4 v172, s[26:27]
	s_add_i32 m0, s34, 0x2000
	s_nop 0
	global_load_lds_dwordx4 v176, s[26:27]
	s_add_u32 s100, vcc_lo, s30
	s_addc_u32 s101, vcc_hi, s31
	s_mov_b32 m0, s22
	s_nop 0
	global_load_lds_dwordx4 v170, s[100:101]
	s_mov_b32 m0, s23
	s_nop 0
	global_load_lds_dwordx4 v174, s[100:101]
	s_waitcnt vmcnt(8)
	s_waitcnt lgkmcnt(0)
	s_barrier
	s_setprio 1
	v_mfma_f32_16x16x32_bf16 v[94:97], v[114:117], v[162:165], v[94:97]
	v_mfma_f32_16x16x32_bf16 v[30:33], v[122:125], v[162:165], v[30:33]
	v_mfma_f32_16x16x32_bf16 v[86:89], v[114:117], v[202:205], v[86:89]
	v_mfma_f32_16x16x32_bf16 v[22:25], v[122:125], v[202:205], v[22:25]
	v_mfma_f32_16x16x32_bf16 v[78:81], v[114:117], v[210:213], v[78:81]
	v_mfma_f32_16x16x32_bf16 v[14:17], v[122:125], v[210:213], v[14:17]
	v_mfma_f32_16x16x32_bf16 v[70:73], v[114:117], v[218:221], v[70:73]
	v_mfma_f32_16x16x32_bf16 v[6:9], v[122:125], v[218:221], v[6:9]
	v_mfma_f32_16x16x32_bf16 v[94:97], v[118:121], v[166:169], v[94:97]
	v_mfma_f32_16x16x32_bf16 v[30:33], v[126:129], v[166:169], v[30:33]
	v_mfma_f32_16x16x32_bf16 v[86:89], v[118:121], v[206:209], v[86:89]
	v_mfma_f32_16x16x32_bf16 v[22:25], v[126:129], v[206:209], v[22:25]
	v_mfma_f32_16x16x32_bf16 v[78:81], v[118:121], v[214:217], v[78:81]
	v_mfma_f32_16x16x32_bf16 v[14:17], v[126:129], v[214:217], v[14:17]
	v_mfma_f32_16x16x32_bf16 v[70:73], v[118:121], v[240:243], v[70:73]
	v_mfma_f32_16x16x32_bf16 v[6:9], v[126:129], v[240:243], v[6:9]
	s_setprio 0
	s_setprio 1
	v_mfma_f32_16x16x32_bf16 v[90:93], v[130:133], v[162:165], v[90:93]
	v_mfma_f32_16x16x32_bf16 v[26:29], v[138:141], v[162:165], v[26:29]
	v_mfma_f32_16x16x32_bf16 v[82:85], v[130:133], v[202:205], v[82:85]
	v_mfma_f32_16x16x32_bf16 v[18:21], v[138:141], v[202:205], v[18:21]
	v_mfma_f32_16x16x32_bf16 v[74:77], v[130:133], v[210:213], v[74:77]
	v_mfma_f32_16x16x32_bf16 v[10:13], v[138:141], v[210:213], v[10:13]
	v_mfma_f32_16x16x32_bf16 v[66:69], v[130:133], v[218:221], v[66:69]
	v_mfma_f32_16x16x32_bf16 v[2:5], v[138:141], v[218:221], v[2:5]
	v_mfma_f32_16x16x32_bf16 v[90:93], v[134:137], v[166:169], v[90:93]
	v_mfma_f32_16x16x32_bf16 v[26:29], v[142:145], v[166:169], v[26:29]
	v_mfma_f32_16x16x32_bf16 v[82:85], v[134:137], v[206:209], v[82:85]
	v_mfma_f32_16x16x32_bf16 v[18:21], v[142:145], v[206:209], v[18:21]
	v_mfma_f32_16x16x32_bf16 v[74:77], v[134:137], v[214:217], v[74:77]
	v_mfma_f32_16x16x32_bf16 v[10:13], v[142:145], v[214:217], v[10:13]
	v_mfma_f32_16x16x32_bf16 v[66:69], v[134:137], v[240:243], v[66:69]
	v_mfma_f32_16x16x32_bf16 v[2:5], v[142:145], v[240:243], v[2:5]
	s_setprio 0
	s_barrier
	s_add_i32 s60, s60, 2
	s_add_u32 s56, s56, 0x100
	s_addc_u32 s57, s57, 0
	s_add_u32 s17, s17, 0x100
	s_addc_u32 s19, s19, 0
	s_cmp_gt_u32 s60, 29
	s_cbranch_scc0 .LBB0_681
	s_and_b64 vcc, exec, s[90:91]
	s_cbranch_vccz .LBB0_686
	s_barrier
	s_and_saveexec_b64 s[26:27], s[40:41]
	s_movk_i32 s60, 0x2c00
	s_cbranch_execnz .LBB0_687

; #define PG8_STAGE(bufoff, gbase, voff) do { _Pragma("unroll") for (int _i = 0; _i < 2; ++_i) \
;         __builtin_amdgcn_global_load_lds((const unsigned*)((const char*)(gbase) + (voff)[_i]), (LAS unsigned*)(lds + (bufoff) + ldsw + _i * 8192), 16, 0, 0); } while (0)
; #define PG8_LDA(dst, b, h) do { _Pragma("unroll") for (int m = 0; m < 4; ++m) _Pragma("unroll") for (int k = 0; k < 2; ++k) dst[m][k] = *(const LAS bf16x8*)(lds + PG8_SA(b, h) + aoff + m * 2048 + k * 1024); } while (0)
; #define PG8_LDB(dst, b, h) do { _Pragma("unroll") for (int n = 0; n < 2; ++n) _Pragma("unroll") for (int k = 0; k < 2; ++k) dst[n][k] = *(const LAS bf16x8*)(lds + PG8_SB(b, h) + boff + n * 2048 + k * 1024); } while (0)
; #define PG8_MMA(ai, bj, At, Bt) do { __builtin_amdgcn_s_setprio(1); _Pragma("unroll") for (int m = 0; m < 4; ++m) _Pragma("unroll") for (int n = 0; n < 2; ++n) _Pragma("unroll") for (int k = 0; k < 2; ++k) \
;         acc[ai][bj][m][n] = __builtin_amdgcn_mfma_f32_16x16x32_bf16(Bt[n][k], At[m][k], acc[ai][bj][m][n], 0, 0, 0); __builtin_amdgcn_s_setprio(0); } while (0)
; #define PG8_WAIT_V(n) asm volatile("s_waitcnt vmcnt(" #n ")" ::: "memory")
; #define PG8_WAIT_L(n) asm volatile("s_waitcnt lgkmcnt(" #n ")" ::: "memory")
; #define PG8_BAR __builtin_amdgcn_s_barrier()
; #define PG8_SCHED __builtin_amdgcn_sched_barrier(0)
; template <class Epi, class Sched>
; __device__ __forceinline__ void gemm_phase(LAS unsigned char* lds, const int lda, const int ldb, const int K, const Sched& S, const Epi& E, int tid) {
;     ...
;             const bool last = (t == nt - 2);
;             const char* a1 = cA + (size_t)(t + 1) * kstep;
;             const char* a2 = last ? nA : cA + (size_t)(t + 2) * kstep; const char* b2 = last ? nB : cB + (size_t)(t + 2) * kstep;
;             const char* a3 = a2 + kstep; const char* b3 = b2 + kstep;
;             PG8_LDB(B0, 0, 0); PG8_LDB(B1, 0, 1); PG8_SCHED; PG8_LDA(At, 0, 0); PG8_STAGE(PG8_SA(1, 1), a1 + hA, voffA);
;             PG8_WAIT_V(8); PG8_WAIT_L(0); PG8_BAR; PG8_MMA(0, 0, At, B0); PG8_MMA(0, 1, At, B1); PG8_BAR; PG8_SCHED;
;             PG8_LDA(At, 0, 1); PG8_STAGE(PG8_SB(0, 0), b2, voffB); PG8_STAGE(PG8_SB(0, 1), b2 + hB, voffB); PG8_STAGE(PG8_SA(0, 0), a2, voffA);
;             PG8_WAIT_V(8); PG8_WAIT_L(0); PG8_BAR; PG8_MMA(1, 0, At, B0); PG8_MMA(1, 1, At, B1); PG8_BAR; PG8_SCHED;
.LBB0_880:
	s_add_u32 s4, s2, 0x100
	s_addc_u32 s5, s3, 0
	s_add_i32 s33, 0, 0x10000
	s_cmpk_eq_i32 s29, 0x54
	s_cselect_b32 s9, s49, s5
	s_cselect_b32 s8, s48, s4
	s_cselect_b32 s7, s51, s28
	s_cselect_b32 s6, s50, s25
	s_add_i32 s34, 0, 0x14000
	v_add_u32_e32 v130, s33, v208
	v_add_u32_e32 v168, s34, v208
	ds_read_b128 v[82:85], v130
	ds_read_b128 v[86:89], v130 offset:1024
	ds_read_b128 v[126:129], v130 offset:2048
	ds_read_b128 v[130:133], v130 offset:3072
	ds_read_b128 v[156:159], v168
	ds_read_b128 v[160:163], v168 offset:1024
	ds_read_b128 v[164:167], v168 offset:2048
	ds_read_b128 v[168:171], v168 offset:3072
	s_add_i32 m0, s15, 0xc000
	ds_read_b128 v[172:175], v210
	ds_read_b128 v[176:179], v210 offset:1024
	ds_read_b128 v[180:183], v210 offset:2048
	ds_read_b128 v[184:187], v210 offset:3072
	ds_read_b128 v[188:191], v210 offset:4096
	ds_read_b128 v[192:195], v210 offset:5120
	ds_read_b128 v[200:203], v210 offset:6144
	ds_read_b128 v[204:207], v210 offset:7168
	global_load_lds_dwordx4 v152, s[2:3]
	s_add_i32 m0, s15, 0xe000
	s_nop 0
	global_load_lds_dwordx4 v154, s[2:3]
	s_waitcnt vmcnt(8)
	s_waitcnt lgkmcnt(0)
	s_barrier
	s_setprio 1
	v_mfma_f32_16x16x32_bf16 v[142:145], v[82:85], v[172:175], v[142:145]
	v_mfma_f32_16x16x32_bf16 v[102:105], v[126:129], v[172:175], v[102:105]
	v_mfma_f32_16x16x32_bf16 v[138:141], v[82:85], v[180:183], v[138:141]
	v_mfma_f32_16x16x32_bf16 v[98:101], v[126:129], v[180:183], v[98:101]
	v_mfma_f32_16x16x32_bf16 v[134:137], v[82:85], v[188:191], v[134:137]
	v_mfma_f32_16x16x32_bf16 v[94:97], v[126:129], v[188:191], v[94:97]
	v_mfma_f32_16x16x32_bf16 v[122:125], v[82:85], v[200:203], v[122:125]
	v_mfma_f32_16x16x32_bf16 v[90:93], v[126:129], v[200:203], v[90:93]
	v_mfma_f32_16x16x32_bf16 v[142:145], v[86:89], v[176:179], v[142:145]
	v_mfma_f32_16x16x32_bf16 v[102:105], v[130:133], v[176:179], v[102:105]
	v_mfma_f32_16x16x32_bf16 v[138:141], v[86:89], v[184:187], v[138:141]
	v_mfma_f32_16x16x32_bf16 v[98:101], v[130:133], v[184:187], v[98:101]
	v_mfma_f32_16x16x32_bf16 v[134:137], v[86:89], v[192:195], v[134:137]
	v_mfma_f32_16x16x32_bf16 v[94:97], v[130:133], v[192:195], v[94:97]
	v_mfma_f32_16x16x32_bf16 v[122:125], v[86:89], v[204:207], v[122:125]
	v_mfma_f32_16x16x32_bf16 v[90:93], v[130:133], v[204:207], v[90:93]
	s_setprio 0
	s_setprio 1
	v_mfma_f32_16x16x32_bf16 v[66:69], v[156:159], v[172:175], v[66:69]
	v_mfma_f32_16x16x32_bf16 v[34:37], v[164:167], v[172:175], v[34:37]
	v_mfma_f32_16x16x32_bf16 v[58:61], v[156:159], v[180:183], v[58:61]
	v_mfma_f32_16x16x32_bf16 v[26:29], v[164:167], v[180:183], v[26:29]
	v_mfma_f32_16x16x32_bf16 v[54:57], v[156:159], v[188:191], v[54:57]
	v_mfma_f32_16x16x32_bf16 v[22:25], v[164:167], v[188:191], v[22:25]
	v_mfma_f32_16x16x32_bf16 v[50:53], v[156:159], v[200:203], v[50:53]
	v_mfma_f32_16x16x32_bf16 v[18:21], v[164:167], v[200:203], v[18:21]
	v_mfma_f32_16x16x32_bf16 v[66:69], v[160:163], v[176:179], v[66:69]
	v_mfma_f32_16x16x32_bf16 v[34:37], v[168:171], v[176:179], v[34:37]
	v_mfma_f32_16x16x32_bf16 v[58:61], v[160:163], v[184:187], v[58:61]
	v_mfma_f32_16x16x32_bf16 v[26:29], v[168:171], v[184:187], v[26:29]
	v_mfma_f32_16x16x32_bf16 v[54:57], v[160:163], v[192:195], v[54:57]
	v_mfma_f32_16x16x32_bf16 v[22:25], v[168:171], v[192:195], v[22:25]
	v_mfma_f32_16x16x32_bf16 v[50:53], v[160:163], v[204:207], v[50:53]
	v_mfma_f32_16x16x32_bf16 v[18:21], v[168:171], v[204:207], v[18:21]
	s_setprio 0
	s_barrier
	s_add_u32 s98, s6, s30
	s_addc_u32 s99, s7, s31
	s_add_u32 s100, s8, s30
	s_addc_u32 s101, s9, s31
	s_add_i32 s2, s33, s14
	s_mov_b32 m0, s2
	ds_read_b128 v[172:175], v210 offset:16384
	ds_read_b128 v[176:179], v210 offset:17408
	ds_read_b128 v[180:183], v210 offset:18432
	ds_read_b128 v[184:187], v210 offset:19456
	ds_read_b128 v[188:191], v210 offset:20480
	ds_read_b128 v[192:195], v210 offset:21504
	ds_read_b128 v[200:203], v210 offset:22528
	ds_read_b128 v[204:207], v210 offset:23552
	global_load_lds_dwordx4 v0, s[6:7]
	s_add_i32 m0, s2, 0x2000
	s_add_u32 s2, s6, 0x160000
	s_addc_u32 s3, s7, 0
	s_add_i32 s33, s34, s14
	global_load_lds_dwordx4 v150, s[6:7]
	s_mov_b32 m0, s33
	s_nop 0
	global_load_lds_dwordx4 v0, s[2:3]
	s_add_i32 m0, s33, 0x2000
	s_nop 0
	global_load_lds_dwordx4 v150, s[2:3]
	s_mov_b32 m0, s15
	s_nop 0
	global_load_lds_dwordx4 v146, s[8:9]
	s_mov_b32 m0, s16
	s_nop 0
	global_load_lds_dwordx4 v148, s[8:9]
	s_waitcnt vmcnt(8)
	s_waitcnt lgkmcnt(0)
	s_barrier
	s_setprio 1
	v_mfma_f32_16x16x32_bf16 v[118:121], v[82:85], v[172:175], v[118:121]
	v_mfma_f32_16x16x32_bf16 v[78:81], v[126:129], v[172:175], v[78:81]
	v_mfma_f32_16x16x32_bf16 v[114:117], v[82:85], v[180:183], v[114:117]
	v_mfma_f32_16x16x32_bf16 v[74:77], v[126:129], v[180:183], v[74:77]
	v_mfma_f32_16x16x32_bf16 v[110:113], v[82:85], v[188:191], v[110:113]
	v_mfma_f32_16x16x32_bf16 v[70:73], v[126:129], v[188:191], v[70:73]
	v_mfma_f32_16x16x32_bf16 v[62:65], v[126:129], v[200:203], v[62:65]
	v_mfma_f32_16x16x32_bf16 v[118:121], v[86:89], v[176:179], v[118:121]
	v_mfma_f32_16x16x32_bf16 v[78:81], v[130:133], v[176:179], v[78:81]
	v_mfma_f32_16x16x32_bf16 v[114:117], v[86:89], v[184:187], v[114:117]
	v_mfma_f32_16x16x32_bf16 v[74:77], v[130:133], v[184:187], v[74:77]
	v_mfma_f32_16x16x32_bf16 v[110:113], v[86:89], v[192:195], v[110:113]
	v_mfma_f32_16x16x32_bf16 v[70:73], v[130:133], v[192:195], v[70:73]
	v_mfma_f32_16x16x32_bf16 v[82:85], v[82:85], v[200:203], v[106:109]
	v_mfma_f32_16x16x32_bf16 v[62:65], v[130:133], v[204:207], v[62:65]
	v_mfma_f32_16x16x32_bf16 v[82:85], v[86:89], v[204:207], v[82:85]
	s_setprio 0
	s_setprio 1
	v_mfma_f32_16x16x32_bf16 v[46:49], v[156:159], v[172:175], v[46:49]
	v_mfma_f32_16x16x32_bf16 v[14:17], v[164:167], v[172:175], v[14:17]
	v_mfma_f32_16x16x32_bf16 v[42:45], v[156:159], v[180:183], v[42:45]
	v_mfma_f32_16x16x32_bf16 v[10:13], v[164:167], v[180:183], v[10:13]
	v_mfma_f32_16x16x32_bf16 v[38:41], v[156:159], v[188:191], v[38:41]
	v_mfma_f32_16x16x32_bf16 v[6:9], v[164:167], v[188:191], v[6:9]
	v_mfma_f32_16x16x32_bf16 v[30:33], v[156:159], v[200:203], v[30:33]
	v_mfma_f32_16x16x32_bf16 v[2:5], v[164:167], v[200:203], v[2:5]
	v_mfma_f32_16x16x32_bf16 v[46:49], v[160:163], v[176:179], v[46:49]
	v_mfma_f32_16x16x32_bf16 v[14:17], v[168:171], v[176:179], v[14:17]
	v_mfma_f32_16x16x32_bf16 v[42:45], v[160:163], v[184:187], v[42:45]
	v_mfma_f32_16x16x32_bf16 v[10:13], v[168:171], v[184:187], v[10:13]
	v_mfma_f32_16x16x32_bf16 v[38:41], v[160:163], v[192:195], v[38:41]
	v_mfma_f32_16x16x32_bf16 v[6:9], v[168:171], v[192:195], v[6:9]
	v_mfma_f32_16x16x32_bf16 v[30:33], v[160:163], v[204:207], v[30:33]
	v_mfma_f32_16x16x32_bf16 v[2:5], v[168:171], v[204:207], v[2:5]
	s_setprio 0
	s_barrier
; #define PG8_STAGE(bufoff, gbase, voff) do { _Pragma("unroll") for (int _i = 0; _i < 2; ++_i) \
;         __builtin_amdgcn_global_load_lds((const unsigned*)((const char*)(gbase) + (voff)[_i]), (LAS unsigned*)(lds + (bufoff) + ldsw + _i * 8192), 16, 0, 0); } while (0)
; #define PG8_LDA(dst, b, h) do { _Pragma("unroll") for (int m = 0; m < 4; ++m) _Pragma("unroll") for (int k = 0; k < 2; ++k) dst[m][k] = *(const LAS bf16x8*)(lds + PG8_SA(b, h) + aoff + m * 2048 + k * 1024); } while (0)
; #define PG8_LDB(dst, b, h) do { _Pragma("unroll") for (int n = 0; n < 2; ++n) _Pragma("unroll") for (int k = 0; k < 2; ++k) dst[n][k] = *(const LAS bf16x8*)(lds + PG8_SB(b, h) + boff + n * 2048 + k * 1024); } while (0)
; #define PG8_MMA(ai, bj, At, Bt) do { __builtin_amdgcn_s_setprio(1); _Pragma("unroll") for (int m = 0; m < 4; ++m) _Pragma("unroll") for (int n = 0; n < 2; ++n) _Pragma("unroll") for (int k = 0; k < 2; ++k) \
;         acc[ai][bj][m][n] = __builtin_amdgcn_mfma_f32_16x16x32_bf16(Bt[n][k], At[m][k], acc[ai][bj][m][n], 0, 0, 0); __builtin_amdgcn_s_setprio(0); } while (0)
; #define PG8_WAIT_V(n) asm volatile("s_waitcnt vmcnt(" #n ")" ::: "memory")
; #define PG8_WAIT_L(n) asm volatile("s_waitcnt lgkmcnt(" #n ")" ::: "memory")
; #define PG8_BAR __builtin_amdgcn_s_barrier()
; #define PG8_SCHED __builtin_amdgcn_sched_barrier(0)
; template <class Epi, class Sched>
; __device__ __forceinline__ void gemm_phase(LAS unsigned char* lds, const int lda, const int ldb, const int K, const Sched& S, const Epi& E, int tid) {
;     ...
;             PG8_LDB(B0, 1, 0); PG8_LDB(B1, 1, 1); PG8_SCHED; PG8_LDA(At, 1, 0); PG8_STAGE(PG8_SA(0, 1), a2 + hA, voffA);
;             PG8_WAIT_V(8); PG8_WAIT_L(0); PG8_BAR; PG8_MMA(0, 0, At, B0); PG8_MMA(0, 1, At, B1); PG8_BAR; PG8_SCHED;
;             PG8_LDA(At, 1, 1); PG8_STAGE(PG8_SB(1, 0), b3, voffB); PG8_STAGE(PG8_SB(1, 1), b3 + hB, voffB); PG8_STAGE(PG8_SA(1, 0), a3, voffA);
;             PG8_WAIT_V(8); PG8_WAIT_L(0); PG8_BAR; PG8_MMA(1, 0, At, B0); PG8_MMA(1, 1, At, B1); PG8_BAR; PG8_SCHED;
;         }
;         if (wr == 0) PG8_BAR;
	s_add_i32 s33, 0, 0x18000
	s_add_i32 s34, 0, 0x1c000
	v_add_u32_e32 v130, s33, v208
	v_add_u32_e32 v168, s34, v208
	ds_read_b128 v[86:89], v130
	ds_read_b128 v[106:109], v130 offset:1024
	ds_read_b128 v[126:129], v130 offset:2048
	ds_read_b128 v[130:133], v130 offset:3072
	ds_read_b128 v[156:159], v168
	ds_read_b128 v[160:163], v168 offset:1024
	ds_read_b128 v[164:167], v168 offset:2048
	ds_read_b128 v[168:171], v168 offset:3072
	s_add_u32 s2, s8, 0x160000
	s_addc_u32 s3, s9, 0
	s_mov_b32 m0, s17
	ds_read_b128 v[172:175], v210 offset:32768
	ds_read_b128 v[176:179], v210 offset:33792
	ds_read_b128 v[180:183], v210 offset:34816
	ds_read_b128 v[184:187], v210 offset:35840
	ds_read_b128 v[188:191], v210 offset:36864
	ds_read_b128 v[192:195], v210 offset:37888
	ds_read_b128 v[200:203], v210 offset:38912
	ds_read_b128 v[204:207], v210 offset:39936
	global_load_lds_dwordx4 v146, s[2:3]
	s_mov_b32 m0, s18
	s_nop 0
	global_load_lds_dwordx4 v148, s[2:3]
	s_waitcnt vmcnt(8)
	s_waitcnt lgkmcnt(0)
	s_barrier
	s_setprio 1
	v_mfma_f32_16x16x32_bf16 v[142:145], v[86:89], v[172:175], v[142:145]
	v_mfma_f32_16x16x32_bf16 v[102:105], v[126:129], v[172:175], v[102:105]
	v_mfma_f32_16x16x32_bf16 v[138:141], v[86:89], v[180:183], v[138:141]
	v_mfma_f32_16x16x32_bf16 v[98:101], v[126:129], v[180:183], v[98:101]
	v_mfma_f32_16x16x32_bf16 v[134:137], v[86:89], v[188:191], v[134:137]
	v_mfma_f32_16x16x32_bf16 v[94:97], v[126:129], v[188:191], v[94:97]
	v_mfma_f32_16x16x32_bf16 v[122:125], v[86:89], v[200:203], v[122:125]
	v_mfma_f32_16x16x32_bf16 v[90:93], v[126:129], v[200:203], v[90:93]
	v_mfma_f32_16x16x32_bf16 v[142:145], v[106:109], v[176:179], v[142:145]
	v_mfma_f32_16x16x32_bf16 v[102:105], v[130:133], v[176:179], v[102:105]
	v_mfma_f32_16x16x32_bf16 v[138:141], v[106:109], v[184:187], v[138:141]
	v_mfma_f32_16x16x32_bf16 v[98:101], v[130:133], v[184:187], v[98:101]
	v_mfma_f32_16x16x32_bf16 v[134:137], v[106:109], v[192:195], v[134:137]
	v_mfma_f32_16x16x32_bf16 v[94:97], v[130:133], v[192:195], v[94:97]
	v_mfma_f32_16x16x32_bf16 v[122:125], v[106:109], v[204:207], v[122:125]
	v_mfma_f32_16x16x32_bf16 v[90:93], v[130:133], v[204:207], v[90:93]
	s_setprio 0
	s_setprio 1
	v_mfma_f32_16x16x32_bf16 v[66:69], v[156:159], v[172:175], v[66:69]
	v_mfma_f32_16x16x32_bf16 v[34:37], v[164:167], v[172:175], v[34:37]
	v_mfma_f32_16x16x32_bf16 v[58:61], v[156:159], v[180:183], v[58:61]
	v_mfma_f32_16x16x32_bf16 v[26:29], v[164:167], v[180:183], v[26:29]
	v_mfma_f32_16x16x32_bf16 v[54:57], v[156:159], v[188:191], v[54:57]
	v_mfma_f32_16x16x32_bf16 v[22:25], v[164:167], v[188:191], v[22:25]
	v_mfma_f32_16x16x32_bf16 v[50:53], v[156:159], v[200:203], v[50:53]
	v_mfma_f32_16x16x32_bf16 v[18:21], v[164:167], v[200:203], v[18:21]
	v_mfma_f32_16x16x32_bf16 v[66:69], v[160:163], v[176:179], v[66:69]
	v_mfma_f32_16x16x32_bf16 v[34:37], v[168:171], v[176:179], v[34:37]
	v_mfma_f32_16x16x32_bf16 v[58:61], v[160:163], v[184:187], v[58:61]
	v_mfma_f32_16x16x32_bf16 v[26:29], v[168:171], v[184:187], v[26:29]
	v_mfma_f32_16x16x32_bf16 v[54:57], v[160:163], v[192:195], v[54:57]
	v_mfma_f32_16x16x32_bf16 v[22:25], v[168:171], v[192:195], v[22:25]
	v_mfma_f32_16x16x32_bf16 v[50:53], v[160:163], v[204:207], v[50:53]
	v_mfma_f32_16x16x32_bf16 v[18:21], v[168:171], v[204:207], v[18:21]
	s_setprio 0
	s_barrier
	s_add_i32 s2, s33, s14
	s_mov_b32 m0, s2
	ds_read_b128 v[172:175], v210 offset:49152
	ds_read_b128 v[176:179], v210 offset:50176
	ds_read_b128 v[180:183], v210 offset:51200
	ds_read_b128 v[184:187], v210 offset:52224
	ds_read_b128 v[188:191], v210 offset:53248
	ds_read_b128 v[192:195], v210 offset:54272
	ds_read_b128 v[200:203], v210 offset:55296
	ds_read_b128 v[204:207], v210 offset:56320
	global_load_lds_dwordx4 v0, s[98:99]
	s_add_i32 m0, s2, 0x2000
	s_add_u32 s2, s6, 0x160080
	s_addc_u32 s3, s7, 0
	s_add_i32 s6, s34, s14
	global_load_lds_dwordx4 v150, s[98:99]
	s_mov_b32 m0, s6
	s_nop 0
	global_load_lds_dwordx4 v0, s[2:3]
	s_add_i32 m0, s6, 0x2000
	s_nop 0
	global_load_lds_dwordx4 v150, s[2:3]
	s_mov_b32 m0, s19
	s_nop 0
	global_load_lds_dwordx4 v146, s[100:101]
	s_mov_b32 m0, s20
	s_nop 0
	global_load_lds_dwordx4 v148, s[100:101]
	s_waitcnt vmcnt(8)
	s_waitcnt lgkmcnt(0)
	s_barrier
	s_setprio 1
	v_mfma_f32_16x16x32_bf16 v[118:121], v[86:89], v[172:175], v[118:121]
	v_mfma_f32_16x16x32_bf16 v[78:81], v[126:129], v[172:175], v[78:81]
	v_mfma_f32_16x16x32_bf16 v[114:117], v[86:89], v[180:183], v[114:117]
	v_mfma_f32_16x16x32_bf16 v[74:77], v[126:129], v[180:183], v[74:77]
	v_mfma_f32_16x16x32_bf16 v[110:113], v[86:89], v[188:191], v[110:113]
	v_mfma_f32_16x16x32_bf16 v[70:73], v[126:129], v[188:191], v[70:73]
	v_mfma_f32_16x16x32_bf16 v[82:85], v[86:89], v[200:203], v[82:85]
	v_mfma_f32_16x16x32_bf16 v[62:65], v[126:129], v[200:203], v[62:65]
	v_mfma_f32_16x16x32_bf16 v[118:121], v[106:109], v[176:179], v[118:121]
	v_mfma_f32_16x16x32_bf16 v[78:81], v[130:133], v[176:179], v[78:81]
	v_mfma_f32_16x16x32_bf16 v[114:117], v[106:109], v[184:187], v[114:117]
	v_mfma_f32_16x16x32_bf16 v[74:77], v[130:133], v[184:187], v[74:77]
	v_mfma_f32_16x16x32_bf16 v[110:113], v[106:109], v[192:195], v[110:113]
	v_mfma_f32_16x16x32_bf16 v[70:73], v[130:133], v[192:195], v[70:73]
	v_mfma_f32_16x16x32_bf16 v[106:109], v[106:109], v[204:207], v[82:85]
	v_mfma_f32_16x16x32_bf16 v[62:65], v[130:133], v[204:207], v[62:65]
	s_setprio 0
	s_setprio 1
	v_mfma_f32_16x16x32_bf16 v[46:49], v[156:159], v[172:175], v[46:49]
	v_mfma_f32_16x16x32_bf16 v[14:17], v[164:167], v[172:175], v[14:17]
	v_mfma_f32_16x16x32_bf16 v[42:45], v[156:159], v[180:183], v[42:45]
	v_mfma_f32_16x16x32_bf16 v[10:13], v[164:167], v[180:183], v[10:13]
	v_mfma_f32_16x16x32_bf16 v[38:41], v[156:159], v[188:191], v[38:41]
	v_mfma_f32_16x16x32_bf16 v[6:9], v[164:167], v[188:191], v[6:9]
	v_mfma_f32_16x16x32_bf16 v[30:33], v[156:159], v[200:203], v[30:33]
	v_mfma_f32_16x16x32_bf16 v[2:5], v[164:167], v[200:203], v[2:5]
	v_mfma_f32_16x16x32_bf16 v[46:49], v[160:163], v[176:179], v[46:49]
	v_mfma_f32_16x16x32_bf16 v[14:17], v[168:171], v[176:179], v[14:17]
	v_mfma_f32_16x16x32_bf16 v[42:45], v[160:163], v[184:187], v[42:45]
	v_mfma_f32_16x16x32_bf16 v[10:13], v[168:171], v[184:187], v[10:13]
	v_mfma_f32_16x16x32_bf16 v[38:41], v[160:163], v[192:195], v[38:41]
	v_mfma_f32_16x16x32_bf16 v[6:9], v[168:171], v[192:195], v[6:9]
	v_mfma_f32_16x16x32_bf16 v[30:33], v[160:163], v[204:207], v[30:33]
	v_mfma_f32_16x16x32_bf16 v[2:5], v[168:171], v[204:207], v[2:5]
	s_setprio 0
	s_barrier
	s_add_i32 s29, s29, 2
	s_add_u32 s25, s25, 0x100
	s_addc_u32 s28, s28, 0
	s_cmpk_gt_u32 s29, 0x55
	s_mov_b64 s[2:3], s[4:5]
	s_cbranch_scc0 .LBB0_880
	s_and_b64 vcc, exec, s[46:47]
	s_cbranch_vccz .LBB0_883
	s_barrier
